# GEMM K-loops: the two k-steps of each accumulator issued back to back
# speedup vs baseline: 1.0202x; 1.0202x over previous
; #define PG8_STAGE(bufoff, gbase, voff) do { _Pragma("unroll") for (int _i = 0; _i < 2; ++_i) \
;         __builtin_amdgcn_global_load_lds((const unsigned*)((const char*)(gbase) + (voff)[_i]), (PG8_LAS unsigned*)(lds + (bufoff) + ldsw + _i * 8192), 16, 0, 0); } while (0)
; #define PG8_LDA(dst, b, h) do { _Pragma("unroll") for (int m = 0; m < 4; ++m) _Pragma("unroll") for (int k = 0; k < 2; ++k) dst[m][k] = *(const PG8_LAS bf16x8*)(lds + PG8_SA(b, h) + aoff + m * 2048 + k * 1024); } while (0)
; #define PG8_LDB(dst, b, h) do { _Pragma("unroll") for (int n = 0; n < 2; ++n) _Pragma("unroll") for (int k = 0; k < 2; ++k) dst[n][k] = *(const PG8_LAS bf16x8*)(lds + PG8_SB(b, h) + boff + n * 2048 + k * 1024); } while (0)
; #define PG8_MMA(ai, bj, At, Bt) do { __builtin_amdgcn_s_setprio(1); _Pragma("unroll") for (int m = 0; m < 4; ++m) _Pragma("unroll") for (int n = 0; n < 2; ++n) _Pragma("unroll") for (int k = 0; k < 2; ++k) \
;         acc[ai][bj][m][n] = __builtin_amdgcn_mfma_f32_16x16x32_bf16(Bt[n][k], At[m][k], acc[ai][bj][m][n], 0, 0, 0); __builtin_amdgcn_s_setprio(0); } while (0)
; #define PG8_WAIT_V(n) asm volatile("s_waitcnt vmcnt(" #n ")" ::: "memory")
; #define PG8_WAIT_L(n) asm volatile("s_waitcnt lgkmcnt(" #n ")" ::: "memory")
; template <class Epi, class Sched, bool ALIGN_EPI = false, bool SP2 = false>
; __device__ __forceinline__ void gemm_phase(PG8_LAS unsigned char* lds, const Gemm g, const Sched& S, const Epi& E) {
;     ...
;             const bool last = (t == nt - 2);
;             const char* a1 = cA + (size_t)(t + 1) * kstep;
;             const char* a2 = last ? nA : cA + (size_t)(t + 2) * kstep; const char* b2 = last ? nB : cB + (size_t)(t + 2) * kstep;
;             const char* a3 = a2 + kstep; const char* b3 = b2 + kstep;
;             if (last && has_next) S.a_ready(nxt);
;             if constexpr (SP2) {
;             PG8_LDB(B0, 0, 0); PG8_LDB(B1, 0, 1); PG8_SCHED; PG8_LDA(At, 0, 0); PG8_STAGE(PG8_SA(1, 1), a1 + hstep, voffA);
;             PG8_WAIT_V(8); PG8_WAIT_L(0); PG8_BAR; PG8_MMA(0, 0, At, B0); PG8_MMA(0, 1, At, B1); PG8_BAR; PG8_SCHED;
;             PG8_LDA(At, 0, 1); PG8_STAGE(PG8_SB(0, 0), b2, voffB); PG8_STAGE(PG8_SB(0, 1), b2 + hstep, voffB); PG8_STAGE(PG8_SA(0, 0), a2, voffA);
;             PG8_WAIT_V(8); PG8_WAIT_L(0); PG8_BAR; PG8_MMA(1, 0, At, B0); PG8_MMA(1, 1, At, B1); PG8_BAR; PG8_SCHED;
.LBB0_132:
	s_add_u32 s18, s46, 0xfffc0080
	s_addc_u32 s38, s47, -1
	s_add_i32 s39, 0, 0x10000
	s_cmp_eq_u32 s85, 12
	s_cselect_b32 s81, s33, s38
	s_cselect_b32 s80, s73, s18
	v_add_u32_e32 v0, s39, v176
	s_cselect_b32 s45, s75, s84
	s_cselect_b32 s44, s82, s83
	s_add_i32 s18, 0, 0x14000
	ds_read_b128 v[144:147], v0
	ds_read_b128 v[148:151], v0 offset:1024
	ds_read_b128 v[152:155], v0 offset:2048
	ds_read_b128 v[156:159], v0 offset:3072
	v_add_u32_e32 v0, s18, v176
	ds_read_b128 v[160:163], v0
	ds_read_b128 v[164:167], v0 offset:1024
	ds_read_b128 v[168:171], v0 offset:2048
	ds_read_b128 v[172:175], v0 offset:3072
	v_lshl_add_u64 v[218:219], s[46:47], 0, v[140:141]
	s_add_i32 m0, s92, 0xc000
	ds_read_b128 v[180:183], v178
	ds_read_b128 v[184:187], v178 offset:1024
	ds_read_b128 v[188:191], v178 offset:2048
	ds_read_b128 v[192:195], v178 offset:3072
	ds_read_b128 v[202:205], v178 offset:4096
	ds_read_b128 v[206:209], v178 offset:5120
	ds_read_b128 v[210:213], v178 offset:6144
	ds_read_b128 v[214:217], v178 offset:7168
	global_load_lds_dwordx4 v[218:219], off
	v_lshl_add_u64 v[218:219], s[46:47], 0, v[142:143]
	s_add_i32 m0, s92, 0xe000
	s_nop 0
	global_load_lds_dwordx4 v[218:219], off
	s_waitcnt vmcnt(8)
	s_waitcnt lgkmcnt(0)
	s_barrier
	s_setprio 1
	s_waitcnt lgkmcnt(0)
	v_mfma_f32_16x16x32_bf16 v[118:121], v[144:147], v[180:183], v[118:121]
	v_mfma_f32_16x16x32_bf16 v[118:121], v[148:151], v[184:187], v[118:121]
	v_mfma_f32_16x16x32_bf16 v[114:117], v[152:155], v[180:183], v[114:117]
	v_mfma_f32_16x16x32_bf16 v[114:117], v[156:159], v[184:187], v[114:117]
	v_mfma_f32_16x16x32_bf16 v[102:105], v[144:147], v[188:191], v[102:105]
	v_mfma_f32_16x16x32_bf16 v[102:105], v[148:151], v[192:195], v[102:105]
	v_mfma_f32_16x16x32_bf16 v[98:101], v[152:155], v[188:191], v[98:101]
	v_mfma_f32_16x16x32_bf16 v[98:101], v[156:159], v[192:195], v[98:101]
	v_mfma_f32_16x16x32_bf16 v[86:89], v[144:147], v[202:205], v[86:89]
	v_mfma_f32_16x16x32_bf16 v[86:89], v[148:151], v[206:209], v[86:89]
	v_mfma_f32_16x16x32_bf16 v[82:85], v[152:155], v[202:205], v[82:85]
	v_mfma_f32_16x16x32_bf16 v[82:85], v[156:159], v[206:209], v[82:85]
	v_mfma_f32_16x16x32_bf16 v[70:73], v[144:147], v[210:213], v[70:73]
	v_mfma_f32_16x16x32_bf16 v[70:73], v[148:151], v[214:217], v[70:73]
	v_mfma_f32_16x16x32_bf16 v[66:69], v[152:155], v[210:213], v[66:69]
	v_mfma_f32_16x16x32_bf16 v[66:69], v[156:159], v[214:217], v[66:69]
	s_setprio 0
	s_setprio 1
	v_mfma_f32_16x16x32_bf16 v[126:129], v[160:163], v[180:183], v[126:129]
	v_mfma_f32_16x16x32_bf16 v[126:129], v[164:167], v[184:187], v[126:129]
	v_mfma_f32_16x16x32_bf16 v[122:125], v[168:171], v[180:183], v[122:125]
	v_mfma_f32_16x16x32_bf16 v[122:125], v[172:175], v[184:187], v[122:125]
	v_mfma_f32_16x16x32_bf16 v[110:113], v[160:163], v[188:191], v[110:113]
	v_mfma_f32_16x16x32_bf16 v[110:113], v[164:167], v[192:195], v[110:113]
	v_mfma_f32_16x16x32_bf16 v[106:109], v[168:171], v[188:191], v[106:109]
	v_mfma_f32_16x16x32_bf16 v[106:109], v[172:175], v[192:195], v[106:109]
	v_mfma_f32_16x16x32_bf16 v[94:97], v[160:163], v[202:205], v[94:97]
	v_mfma_f32_16x16x32_bf16 v[94:97], v[164:167], v[206:209], v[94:97]
	v_mfma_f32_16x16x32_bf16 v[90:93], v[168:171], v[202:205], v[90:93]
	v_mfma_f32_16x16x32_bf16 v[90:93], v[172:175], v[206:209], v[90:93]
	v_mfma_f32_16x16x32_bf16 v[78:81], v[160:163], v[210:213], v[78:81]
	v_mfma_f32_16x16x32_bf16 v[78:81], v[164:167], v[214:217], v[78:81]
	v_mfma_f32_16x16x32_bf16 v[74:77], v[168:171], v[210:213], v[74:77]
	v_mfma_f32_16x16x32_bf16 v[74:77], v[172:175], v[214:217], v[74:77]
	s_setprio 0
	s_barrier
	s_add_i32 s38, s39, s91
	v_lshl_add_u64 v[218:219], s[44:45], 0, v[134:135]
	s_mov_b32 m0, s38
	ds_read_b128 v[180:183], v178 offset:16384
	ds_read_b128 v[184:187], v178 offset:17408
	ds_read_b128 v[188:191], v178 offset:18432
	ds_read_b128 v[192:195], v178 offset:19456
	ds_read_b128 v[202:205], v178 offset:20480
	ds_read_b128 v[206:209], v178 offset:21504
	ds_read_b128 v[210:213], v178 offset:22528
	ds_read_b128 v[214:217], v178 offset:23552
	global_load_lds_dwordx4 v[218:219], off
	s_add_i32 m0, s38, 0x2000
	s_add_u32 s38, s44, 0x40000
	v_lshl_add_u64 v[220:221], s[44:45], 0, v[130:131]
	s_addc_u32 s39, s45, 0
	s_add_i32 s18, s18, s91
	global_load_lds_dwordx4 v[220:221], off
	v_lshl_add_u64 v[222:223], s[38:39], 0, v[134:135]
	s_mov_b32 m0, s18
	v_lshl_add_u64 v[224:225], s[80:81], 0, v[132:133]
	global_load_lds_dwordx4 v[222:223], off
	v_lshl_add_u64 v[222:223], s[38:39], 0, v[130:131]
	s_add_i32 m0, s18, 0x2000
	s_nop 0
	global_load_lds_dwordx4 v[222:223], off
	v_lshl_add_u64 v[222:223], s[80:81], 0, v[136:137]
	s_mov_b32 m0, s92
	s_nop 0
	global_load_lds_dwordx4 v[222:223], off
	s_mov_b32 m0, s93
	s_nop 0
	global_load_lds_dwordx4 v[224:225], off
	s_waitcnt vmcnt(8)
	s_waitcnt lgkmcnt(0)
	s_barrier
; #define PG8_STAGE(bufoff, gbase, voff) do { _Pragma("unroll") for (int _i = 0; _i < 2; ++_i) \
;         __builtin_amdgcn_global_load_lds((const unsigned*)((const char*)(gbase) + (voff)[_i]), (PG8_LAS unsigned*)(lds + (bufoff) + ldsw + _i * 8192), 16, 0, 0); } while (0)
; #define PG8_LDA(dst, b, h) do { _Pragma("unroll") for (int m = 0; m < 4; ++m) _Pragma("unroll") for (int k = 0; k < 2; ++k) dst[m][k] = *(const PG8_LAS bf16x8*)(lds + PG8_SA(b, h) + aoff + m * 2048 + k * 1024); } while (0)
; #define PG8_LDB(dst, b, h) do { _Pragma("unroll") for (int n = 0; n < 2; ++n) _Pragma("unroll") for (int k = 0; k < 2; ++k) dst[n][k] = *(const PG8_LAS bf16x8*)(lds + PG8_SB(b, h) + boff + n * 2048 + k * 1024); } while (0)
; #define PG8_MMA(ai, bj, At, Bt) do { __builtin_amdgcn_s_setprio(1); _Pragma("unroll") for (int m = 0; m < 4; ++m) _Pragma("unroll") for (int n = 0; n < 2; ++n) _Pragma("unroll") for (int k = 0; k < 2; ++k) \
;         acc[ai][bj][m][n] = __builtin_amdgcn_mfma_f32_16x16x32_bf16(Bt[n][k], At[m][k], acc[ai][bj][m][n], 0, 0, 0); __builtin_amdgcn_s_setprio(0); } while (0)
; #define PG8_WAIT_V(n) asm volatile("s_waitcnt vmcnt(" #n ")" ::: "memory")
; #define PG8_WAIT_L(n) asm volatile("s_waitcnt lgkmcnt(" #n ")" ::: "memory")
; #define PG8_BAR __builtin_amdgcn_s_barrier()
; #define PG8_SCHED __builtin_amdgcn_sched_barrier(0)
; template <class Epi, class Sched, bool ALIGN_EPI = false, bool SP2 = false>
; __device__ __forceinline__ void gemm_phase(PG8_LAS unsigned char* lds, const Gemm g, const Sched& S, const Epi& E) {
;     ...
;             PG8_WAIT_V(8); PG8_WAIT_L(0); PG8_BAR; PG8_MMA(1, 0, At, B0); PG8_MMA(1, 1, At, B1); PG8_BAR; PG8_SCHED;
;             PG8_LDB(B0, 1, 0); PG8_LDB(B1, 1, 1); PG8_SCHED; PG8_LDA(At, 1, 0); PG8_STAGE(PG8_SA(0, 1), a2 + hstep, voffA);
;             PG8_WAIT_V(8); PG8_WAIT_L(0); PG8_BAR; PG8_MMA(0, 0, At, B0); PG8_MMA(0, 1, At, B1); PG8_BAR; PG8_SCHED;
	s_setprio 1
	s_waitcnt lgkmcnt(0)
	v_mfma_f32_16x16x32_bf16 v[54:57], v[144:147], v[180:183], v[54:57]
	v_mfma_f32_16x16x32_bf16 v[54:57], v[148:151], v[184:187], v[54:57]
	v_mfma_f32_16x16x32_bf16 v[50:53], v[152:155], v[180:183], v[50:53]
	v_mfma_f32_16x16x32_bf16 v[50:53], v[156:159], v[184:187], v[50:53]
	v_mfma_f32_16x16x32_bf16 v[38:41], v[144:147], v[188:191], v[38:41]
	v_mfma_f32_16x16x32_bf16 v[38:41], v[148:151], v[192:195], v[38:41]
	v_mfma_f32_16x16x32_bf16 v[34:37], v[152:155], v[188:191], v[34:37]
	v_mfma_f32_16x16x32_bf16 v[34:37], v[156:159], v[192:195], v[34:37]
	v_mfma_f32_16x16x32_bf16 v[22:25], v[144:147], v[202:205], v[22:25]
	v_mfma_f32_16x16x32_bf16 v[22:25], v[148:151], v[206:209], v[22:25]
	v_mfma_f32_16x16x32_bf16 v[18:21], v[152:155], v[202:205], v[18:21]
	v_mfma_f32_16x16x32_bf16 v[18:21], v[156:159], v[206:209], v[18:21]
	v_mfma_f32_16x16x32_bf16 v[6:9], v[144:147], v[210:213], v[6:9]
	v_mfma_f32_16x16x32_bf16 v[6:9], v[148:151], v[214:217], v[6:9]
	v_mfma_f32_16x16x32_bf16 v[2:5], v[152:155], v[210:213], v[2:5]
	v_mfma_f32_16x16x32_bf16 v[2:5], v[156:159], v[214:217], v[2:5]
	s_setprio 0
	s_setprio 1
	v_mfma_f32_16x16x32_bf16 v[62:65], v[160:163], v[180:183], v[62:65]
	v_mfma_f32_16x16x32_bf16 v[62:65], v[164:167], v[184:187], v[62:65]
	v_mfma_f32_16x16x32_bf16 v[58:61], v[168:171], v[180:183], v[58:61]
	v_mfma_f32_16x16x32_bf16 v[58:61], v[172:175], v[184:187], v[58:61]
	v_mfma_f32_16x16x32_bf16 v[46:49], v[160:163], v[188:191], v[46:49]
	v_mfma_f32_16x16x32_bf16 v[46:49], v[164:167], v[192:195], v[46:49]
	v_mfma_f32_16x16x32_bf16 v[42:45], v[168:171], v[188:191], v[42:45]
	v_mfma_f32_16x16x32_bf16 v[42:45], v[172:175], v[192:195], v[42:45]
	v_mfma_f32_16x16x32_bf16 v[30:33], v[160:163], v[202:205], v[30:33]
	v_mfma_f32_16x16x32_bf16 v[30:33], v[164:167], v[206:209], v[30:33]
	v_mfma_f32_16x16x32_bf16 v[26:29], v[168:171], v[202:205], v[26:29]
	v_mfma_f32_16x16x32_bf16 v[26:29], v[172:175], v[206:209], v[26:29]
	v_mfma_f32_16x16x32_bf16 v[10:13], v[160:163], v[210:213], v[10:13]
	v_mfma_f32_16x16x32_bf16 v[10:13], v[164:167], v[214:217], v[10:13]
	v_mfma_f32_16x16x32_bf16 v[14:17], v[168:171], v[210:213], v[14:17]
	v_mfma_f32_16x16x32_bf16 v[14:17], v[172:175], v[214:217], v[14:17]
	s_setprio 0
	s_barrier
	s_add_i32 s18, 0, 0x18000
	v_add_u32_e32 v0, s18, v176
	s_add_i32 vcc_lo, 0, 0x1c000
	ds_read_b128 v[144:147], v0
	ds_read_b128 v[148:151], v0 offset:1024
	ds_read_b128 v[152:155], v0 offset:2048
	ds_read_b128 v[156:159], v0 offset:3072
	v_add_u32_e32 v0, vcc_lo, v176
	ds_read_b128 v[160:163], v0
	ds_read_b128 v[164:167], v0 offset:1024
	ds_read_b128 v[168:171], v0 offset:2048
	ds_read_b128 v[172:175], v0 offset:3072
	s_add_u32 s38, s80, 0x40000
	s_addc_u32 s39, s81, 0
	s_mov_b32 m0, s94
	v_lshl_add_u64 v[226:227], s[38:39], 0, v[136:137]
	ds_read_b128 v[180:183], v178 offset:32768
	ds_read_b128 v[184:187], v178 offset:33792
	ds_read_b128 v[188:191], v178 offset:34816
	ds_read_b128 v[192:195], v178 offset:35840
	ds_read_b128 v[202:205], v178 offset:36864
	ds_read_b128 v[206:209], v178 offset:37888
	ds_read_b128 v[210:213], v178 offset:38912
	ds_read_b128 v[214:217], v178 offset:39936
	global_load_lds_dwordx4 v[226:227], off
	v_lshl_add_u64 v[226:227], s[38:39], 0, v[132:133]
	s_mov_b32 m0, s95
	s_nop 0
	global_load_lds_dwordx4 v[226:227], off
	s_waitcnt vmcnt(8)
	s_waitcnt lgkmcnt(0)
	s_barrier
	s_setprio 1
	s_waitcnt lgkmcnt(0)
	v_mfma_f32_16x16x32_bf16 v[118:121], v[144:147], v[180:183], v[118:121]
	v_mfma_f32_16x16x32_bf16 v[118:121], v[148:151], v[184:187], v[118:121]
	v_mfma_f32_16x16x32_bf16 v[114:117], v[152:155], v[180:183], v[114:117]
	v_mfma_f32_16x16x32_bf16 v[114:117], v[156:159], v[184:187], v[114:117]
	v_mfma_f32_16x16x32_bf16 v[102:105], v[144:147], v[188:191], v[102:105]
	v_mfma_f32_16x16x32_bf16 v[102:105], v[148:151], v[192:195], v[102:105]
	v_mfma_f32_16x16x32_bf16 v[98:101], v[152:155], v[188:191], v[98:101]
	v_mfma_f32_16x16x32_bf16 v[98:101], v[156:159], v[192:195], v[98:101]
	v_mfma_f32_16x16x32_bf16 v[86:89], v[144:147], v[202:205], v[86:89]
	v_mfma_f32_16x16x32_bf16 v[86:89], v[148:151], v[206:209], v[86:89]
	v_mfma_f32_16x16x32_bf16 v[82:85], v[152:155], v[202:205], v[82:85]
	v_mfma_f32_16x16x32_bf16 v[82:85], v[156:159], v[206:209], v[82:85]
	v_mfma_f32_16x16x32_bf16 v[70:73], v[144:147], v[210:213], v[70:73]
	v_mfma_f32_16x16x32_bf16 v[70:73], v[148:151], v[214:217], v[70:73]
	v_mfma_f32_16x16x32_bf16 v[66:69], v[152:155], v[210:213], v[66:69]
	v_mfma_f32_16x16x32_bf16 v[66:69], v[156:159], v[214:217], v[66:69]
	s_setprio 0
	s_setprio 1
	v_mfma_f32_16x16x32_bf16 v[126:129], v[160:163], v[180:183], v[126:129]
	v_mfma_f32_16x16x32_bf16 v[126:129], v[164:167], v[184:187], v[126:129]
	v_mfma_f32_16x16x32_bf16 v[122:125], v[168:171], v[180:183], v[122:125]
	v_mfma_f32_16x16x32_bf16 v[122:125], v[172:175], v[184:187], v[122:125]
	v_mfma_f32_16x16x32_bf16 v[110:113], v[160:163], v[188:191], v[110:113]
	v_mfma_f32_16x16x32_bf16 v[110:113], v[164:167], v[192:195], v[110:113]
	v_mfma_f32_16x16x32_bf16 v[106:109], v[168:171], v[188:191], v[106:109]
	v_mfma_f32_16x16x32_bf16 v[106:109], v[172:175], v[192:195], v[106:109]
	v_mfma_f32_16x16x32_bf16 v[94:97], v[160:163], v[202:205], v[94:97]
	v_mfma_f32_16x16x32_bf16 v[94:97], v[164:167], v[206:209], v[94:97]
	v_mfma_f32_16x16x32_bf16 v[90:93], v[168:171], v[202:205], v[90:93]
	v_mfma_f32_16x16x32_bf16 v[90:93], v[172:175], v[206:209], v[90:93]
	v_mfma_f32_16x16x32_bf16 v[78:81], v[160:163], v[210:213], v[78:81]
	v_mfma_f32_16x16x32_bf16 v[78:81], v[164:167], v[214:217], v[78:81]
	v_mfma_f32_16x16x32_bf16 v[74:77], v[168:171], v[210:213], v[74:77]
	v_mfma_f32_16x16x32_bf16 v[74:77], v[172:175], v[214:217], v[74:77]
	s_setprio 0
	s_barrier
; #define PG8_STAGE(bufoff, gbase, voff) do { _Pragma("unroll") for (int _i = 0; _i < 2; ++_i) \
;         __builtin_amdgcn_global_load_lds((const unsigned*)((const char*)(gbase) + (voff)[_i]), (PG8_LAS unsigned*)(lds + (bufoff) + ldsw + _i * 8192), 16, 0, 0); } while (0)
; #define PG8_LDA(dst, b, h) do { _Pragma("unroll") for (int m = 0; m < 4; ++m) _Pragma("unroll") for (int k = 0; k < 2; ++k) dst[m][k] = *(const PG8_LAS bf16x8*)(lds + PG8_SA(b, h) + aoff + m * 2048 + k * 1024); } while (0)
; #define PG8_MMA(ai, bj, At, Bt) do { __builtin_amdgcn_s_setprio(1); _Pragma("unroll") for (int m = 0; m < 4; ++m) _Pragma("unroll") for (int n = 0; n < 2; ++n) _Pragma("unroll") for (int k = 0; k < 2; ++k) \
;         acc[ai][bj][m][n] = __builtin_amdgcn_mfma_f32_16x16x32_bf16(Bt[n][k], At[m][k], acc[ai][bj][m][n], 0, 0, 0); __builtin_amdgcn_s_setprio(0); } while (0)
; #define PG8_WAIT_V(n) asm volatile("s_waitcnt vmcnt(" #n ")" ::: "memory")
; #define PG8_WAIT_L(n) asm volatile("s_waitcnt lgkmcnt(" #n ")" ::: "memory")
; #define PG8_BAR __builtin_amdgcn_s_barrier()
; #define PG8_SCHED __builtin_amdgcn_sched_barrier(0)
; template <class Epi, class Sched, bool ALIGN_EPI = false, bool SP2 = false>
; __device__ __forceinline__ void gemm_phase(PG8_LAS unsigned char* lds, const Gemm g, const Sched& S, const Epi& E) {
;     ...
;         for (int t = 0; t < nt; t += 2) {
;             const bool last = (t == nt - 2);
;             const char* a1 = cA + (size_t)(t + 1) * kstep;
;             const char* a2 = last ? nA : cA + (size_t)(t + 2) * kstep; const char* b2 = last ? nB : cB + (size_t)(t + 2) * kstep;
;             const char* a3 = a2 + kstep; const char* b3 = b2 + kstep;
;             if (last && has_next) S.a_ready(nxt);
;     ...
;             PG8_LDA(At, 1, 1); PG8_STAGE(PG8_SB(1, 0), b3, voffB); PG8_STAGE(PG8_SB(1, 1), b3 + hstep, voffB); PG8_STAGE(PG8_SA(1, 0), a3, voffA);
;             PG8_WAIT_V(8); PG8_WAIT_L(0); PG8_BAR; PG8_MMA(1, 0, At, B0); PG8_MMA(1, 1, At, B1); PG8_BAR; PG8_SCHED;
	s_add_i32 s18, s18, s91
	v_lshl_add_u64 v[218:219], v[218:219], 0, s[30:31]
	s_mov_b32 m0, s18
	ds_read_b128 v[180:183], v178 offset:49152
	ds_read_b128 v[184:187], v178 offset:50176
	ds_read_b128 v[188:191], v178 offset:51200
	ds_read_b128 v[192:195], v178 offset:52224
	ds_read_b128 v[202:205], v178 offset:53248
	ds_read_b128 v[206:209], v178 offset:54272
	ds_read_b128 v[210:213], v178 offset:55296
	ds_read_b128 v[214:217], v178 offset:56320
	global_load_lds_dwordx4 v[218:219], off
	s_add_i32 m0, s18, 0x2000
	s_add_u32 s38, s44, 0x40080
	v_lshl_add_u64 v[218:219], v[220:221], 0, s[30:31]
	s_addc_u32 s39, s45, 0
	s_add_i32 s18, vcc_lo, s91
	global_load_lds_dwordx4 v[218:219], off
	v_lshl_add_u64 v[218:219], s[38:39], 0, v[134:135]
	s_mov_b32 m0, s18
	s_nop 0
	global_load_lds_dwordx4 v[218:219], off
	v_lshl_add_u64 v[218:219], s[38:39], 0, v[130:131]
	s_add_i32 m0, s18, 0x2000
	s_nop 0
	global_load_lds_dwordx4 v[218:219], off
	v_lshl_add_u64 v[218:219], v[222:223], 0, s[30:31]
	s_mov_b32 m0, s7
	s_nop 0
	global_load_lds_dwordx4 v[218:219], off
	v_lshl_add_u64 v[218:219], v[224:225], 0, s[30:31]
	s_mov_b32 m0, s96
	s_nop 0
	global_load_lds_dwordx4 v[218:219], off
	s_waitcnt vmcnt(8)
	s_waitcnt lgkmcnt(0)
	s_barrier
	s_setprio 1
	s_waitcnt lgkmcnt(0)
	v_mfma_f32_16x16x32_bf16 v[54:57], v[144:147], v[180:183], v[54:57]
	v_mfma_f32_16x16x32_bf16 v[54:57], v[148:151], v[184:187], v[54:57]
	v_mfma_f32_16x16x32_bf16 v[50:53], v[152:155], v[180:183], v[50:53]
	v_mfma_f32_16x16x32_bf16 v[50:53], v[156:159], v[184:187], v[50:53]
	v_mfma_f32_16x16x32_bf16 v[38:41], v[144:147], v[188:191], v[38:41]
	v_mfma_f32_16x16x32_bf16 v[38:41], v[148:151], v[192:195], v[38:41]
	v_mfma_f32_16x16x32_bf16 v[34:37], v[152:155], v[188:191], v[34:37]
	v_mfma_f32_16x16x32_bf16 v[34:37], v[156:159], v[192:195], v[34:37]
	v_mfma_f32_16x16x32_bf16 v[22:25], v[144:147], v[202:205], v[22:25]
	v_mfma_f32_16x16x32_bf16 v[22:25], v[148:151], v[206:209], v[22:25]
	v_mfma_f32_16x16x32_bf16 v[18:21], v[152:155], v[202:205], v[18:21]
	v_mfma_f32_16x16x32_bf16 v[18:21], v[156:159], v[206:209], v[18:21]
	v_mfma_f32_16x16x32_bf16 v[6:9], v[144:147], v[210:213], v[6:9]
	v_mfma_f32_16x16x32_bf16 v[6:9], v[148:151], v[214:217], v[6:9]
	v_mfma_f32_16x16x32_bf16 v[2:5], v[152:155], v[210:213], v[2:5]
	v_mfma_f32_16x16x32_bf16 v[2:5], v[156:159], v[214:217], v[2:5]
	s_setprio 0
	s_setprio 1
	v_mfma_f32_16x16x32_bf16 v[62:65], v[160:163], v[180:183], v[62:65]
	v_mfma_f32_16x16x32_bf16 v[62:65], v[164:167], v[184:187], v[62:65]
	v_mfma_f32_16x16x32_bf16 v[58:61], v[168:171], v[180:183], v[58:61]
	v_mfma_f32_16x16x32_bf16 v[58:61], v[172:175], v[184:187], v[58:61]
	v_mfma_f32_16x16x32_bf16 v[46:49], v[160:163], v[188:191], v[46:49]
	v_mfma_f32_16x16x32_bf16 v[46:49], v[164:167], v[192:195], v[46:49]
	v_mfma_f32_16x16x32_bf16 v[42:45], v[168:171], v[188:191], v[42:45]
	v_mfma_f32_16x16x32_bf16 v[42:45], v[172:175], v[192:195], v[42:45]
	v_mfma_f32_16x16x32_bf16 v[30:33], v[160:163], v[202:205], v[30:33]
	v_mfma_f32_16x16x32_bf16 v[30:33], v[164:167], v[206:209], v[30:33]
	v_mfma_f32_16x16x32_bf16 v[26:29], v[168:171], v[202:205], v[26:29]
	v_mfma_f32_16x16x32_bf16 v[26:29], v[172:175], v[206:209], v[26:29]
	v_mfma_f32_16x16x32_bf16 v[10:13], v[160:163], v[210:213], v[10:13]
	v_mfma_f32_16x16x32_bf16 v[10:13], v[164:167], v[214:217], v[10:13]
	v_mfma_f32_16x16x32_bf16 v[14:17], v[168:171], v[210:213], v[14:17]
	v_mfma_f32_16x16x32_bf16 v[14:17], v[172:175], v[214:217], v[14:17]
	s_setprio 0
	s_barrier
	s_add_i32 s85, s85, 2
	s_add_u32 s46, s46, 0x100
	s_addc_u32 s47, s47, 0
	s_add_u32 s83, s83, 0x100
	s_addc_u32 s84, s84, 0
	s_cmp_gt_u32 s85, 13
	s_cbranch_scc0 .LBB0_132
	s_and_b64 vcc, exec, s[10:11]
	s_cbranch_vccz .LBB0_135
	s_barrier

; #define PG8_STAGE(bufoff, gbase, voff) do { _Pragma("unroll") for (int _i = 0; _i < 2; ++_i) \
;         __builtin_amdgcn_global_load_lds((const unsigned*)((const char*)(gbase) + (voff)[_i]), (PG8_LAS unsigned*)(lds + (bufoff) + ldsw + _i * 8192), 16, 0, 0); } while (0)
; #define PG8_LDA(dst, b, h) do { _Pragma("unroll") for (int m = 0; m < 4; ++m) _Pragma("unroll") for (int k = 0; k < 2; ++k) dst[m][k] = *(const PG8_LAS bf16x8*)(lds + PG8_SA(b, h) + aoff + m * 2048 + k * 1024); } while (0)
; #define PG8_LDB(dst, b, h) do { _Pragma("unroll") for (int n = 0; n < 2; ++n) _Pragma("unroll") for (int k = 0; k < 2; ++k) dst[n][k] = *(const PG8_LAS bf16x8*)(lds + PG8_SB(b, h) + boff + n * 2048 + k * 1024); } while (0)
; #define PG8_MMA(ai, bj, At, Bt) do { __builtin_amdgcn_s_setprio(1); _Pragma("unroll") for (int m = 0; m < 4; ++m) _Pragma("unroll") for (int n = 0; n < 2; ++n) _Pragma("unroll") for (int k = 0; k < 2; ++k) \
;         acc[ai][bj][m][n] = __builtin_amdgcn_mfma_f32_16x16x32_bf16(Bt[n][k], At[m][k], acc[ai][bj][m][n], 0, 0, 0); __builtin_amdgcn_s_setprio(0); } while (0)
; #define PG8_WAIT_V(n) asm volatile("s_waitcnt vmcnt(" #n ")" ::: "memory")
; #define PG8_WAIT_L(n) asm volatile("s_waitcnt lgkmcnt(" #n ")" ::: "memory")
; template <class Epi, class Sched, bool ALIGN_EPI = false, bool SP2 = false>
; __device__ __forceinline__ void gemm_phase(PG8_LAS unsigned char* lds, const Gemm g, const Sched& S, const Epi& E) {
;     ...
;             const bool last = (t == nt - 2);
;             const char* a1 = cA + (size_t)(t + 1) * kstep;
;             const char* a2 = last ? nA : cA + (size_t)(t + 2) * kstep; const char* b2 = last ? nB : cB + (size_t)(t + 2) * kstep;
;             const char* a3 = a2 + kstep; const char* b3 = b2 + kstep;
;             if (last && has_next) S.a_ready(nxt);
;             if constexpr (SP2) {
;             PG8_LDB(B0, 0, 0); PG8_LDB(B1, 0, 1); PG8_SCHED; PG8_LDA(At, 0, 0); PG8_STAGE(PG8_SA(1, 1), a1 + hstep, voffA);
;             PG8_WAIT_V(8); PG8_WAIT_L(0); PG8_BAR; PG8_MMA(0, 0, At, B0); PG8_MMA(0, 1, At, B1); PG8_BAR; PG8_SCHED;
;             PG8_LDA(At, 0, 1); PG8_STAGE(PG8_SB(0, 0), b2, voffB); PG8_STAGE(PG8_SB(0, 1), b2 + hstep, voffB); PG8_STAGE(PG8_SA(0, 0), a2, voffA);
;             PG8_WAIT_V(8); PG8_WAIT_L(0); PG8_BAR; PG8_MMA(1, 0, At, B0); PG8_MMA(1, 1, At, B1); PG8_BAR; PG8_SCHED;
.LBB0_220:
	s_add_u32 s18, s60, 0xfffc0080
	s_addc_u32 s38, s61, -1
	s_add_i32 s39, 0, 0x10000
	s_cmp_eq_u32 s82, 12
	s_cselect_b32 s65, s47, s38
	s_cselect_b32 s64, s78, s18
	v_add_u32_e32 v145, s39, v141
	s_cselect_b32 s57, s49, s81
	s_cselect_b32 s56, s79, s80
	s_add_i32 s18, 0, 0x14000
	ds_read_b128 v[146:149], v145
	ds_read_b128 v[150:153], v145 offset:1024
	ds_read_b128 v[154:157], v145 offset:2048
	ds_read_b128 v[158:161], v145 offset:3072
	v_add_u32_e32 v145, s18, v141
	ds_read_b128 v[162:165], v145
	ds_read_b128 v[166:169], v145 offset:1024
	ds_read_b128 v[170:173], v145 offset:2048
	ds_read_b128 v[174:177], v145 offset:3072
	v_lshl_add_u64 v[194:195], s[60:61], 0, v[136:137]
	s_add_i32 m0, s29, 0xc000
	ds_read_b128 v[178:181], v144
	ds_read_b128 v[182:185], v144 offset:1024
	ds_read_b128 v[186:189], v144 offset:2048
	ds_read_b128 v[190:193], v144 offset:3072
	ds_read_b128 v[202:205], v144 offset:4096
	ds_read_b128 v[206:209], v144 offset:5120
	ds_read_b128 v[210:213], v144 offset:6144
	ds_read_b128 v[214:217], v144 offset:7168
	global_load_lds_dwordx4 v[194:195], off
	v_lshl_add_u64 v[194:195], s[60:61], 0, v[138:139]
	s_add_i32 m0, s29, 0xe000
	s_nop 0
	global_load_lds_dwordx4 v[194:195], off
	s_waitcnt vmcnt(8)
	s_waitcnt lgkmcnt(0)
	s_barrier
	s_setprio 1
	s_waitcnt lgkmcnt(0)
	v_mfma_f32_16x16x32_bf16 v[114:117], v[146:149], v[178:181], v[114:117]
	v_mfma_f32_16x16x32_bf16 v[114:117], v[150:153], v[182:185], v[114:117]
	v_mfma_f32_16x16x32_bf16 v[118:121], v[154:157], v[178:181], v[118:121]
	v_mfma_f32_16x16x32_bf16 v[118:121], v[158:161], v[182:185], v[118:121]
	v_mfma_f32_16x16x32_bf16 v[98:101], v[146:149], v[186:189], v[98:101]
	v_mfma_f32_16x16x32_bf16 v[98:101], v[150:153], v[190:193], v[98:101]
	v_mfma_f32_16x16x32_bf16 v[102:105], v[154:157], v[186:189], v[102:105]
	v_mfma_f32_16x16x32_bf16 v[102:105], v[158:161], v[190:193], v[102:105]
	v_mfma_f32_16x16x32_bf16 v[82:85], v[146:149], v[202:205], v[82:85]
	v_mfma_f32_16x16x32_bf16 v[82:85], v[150:153], v[206:209], v[82:85]
	v_mfma_f32_16x16x32_bf16 v[86:89], v[154:157], v[202:205], v[86:89]
	v_mfma_f32_16x16x32_bf16 v[86:89], v[158:161], v[206:209], v[86:89]
	v_mfma_f32_16x16x32_bf16 v[66:69], v[146:149], v[210:213], v[66:69]
	v_mfma_f32_16x16x32_bf16 v[66:69], v[150:153], v[214:217], v[66:69]
	v_mfma_f32_16x16x32_bf16 v[70:73], v[154:157], v[210:213], v[70:73]
	v_mfma_f32_16x16x32_bf16 v[70:73], v[158:161], v[214:217], v[70:73]
	s_setprio 0
	s_setprio 1
	v_mfma_f32_16x16x32_bf16 v[122:125], v[162:165], v[178:181], v[122:125]
	v_mfma_f32_16x16x32_bf16 v[122:125], v[166:169], v[182:185], v[122:125]
	v_mfma_f32_16x16x32_bf16 v[126:129], v[170:173], v[178:181], v[126:129]
	v_mfma_f32_16x16x32_bf16 v[126:129], v[174:177], v[182:185], v[126:129]
	v_mfma_f32_16x16x32_bf16 v[106:109], v[162:165], v[186:189], v[106:109]
	v_mfma_f32_16x16x32_bf16 v[106:109], v[166:169], v[190:193], v[106:109]
	v_mfma_f32_16x16x32_bf16 v[110:113], v[170:173], v[186:189], v[110:113]
	v_mfma_f32_16x16x32_bf16 v[110:113], v[174:177], v[190:193], v[110:113]
	v_mfma_f32_16x16x32_bf16 v[90:93], v[162:165], v[202:205], v[90:93]
	v_mfma_f32_16x16x32_bf16 v[90:93], v[166:169], v[206:209], v[90:93]
	v_mfma_f32_16x16x32_bf16 v[94:97], v[170:173], v[202:205], v[94:97]
	v_mfma_f32_16x16x32_bf16 v[94:97], v[174:177], v[206:209], v[94:97]
	v_mfma_f32_16x16x32_bf16 v[74:77], v[162:165], v[210:213], v[74:77]
	v_mfma_f32_16x16x32_bf16 v[74:77], v[166:169], v[214:217], v[74:77]
	v_mfma_f32_16x16x32_bf16 v[78:81], v[170:173], v[210:213], v[78:81]
	v_mfma_f32_16x16x32_bf16 v[78:81], v[174:177], v[214:217], v[78:81]
	s_setprio 0
	s_barrier
	s_add_i32 s38, s39, s27
	v_lshl_add_u64 v[194:195], s[56:57], 0, v[0:1]
	s_mov_b32 m0, s38
	ds_read_b128 v[178:181], v144 offset:16384
	ds_read_b128 v[182:185], v144 offset:17408
	ds_read_b128 v[186:189], v144 offset:18432
	ds_read_b128 v[190:193], v144 offset:19456
	ds_read_b128 v[202:205], v144 offset:20480
	ds_read_b128 v[206:209], v144 offset:21504
	ds_read_b128 v[210:213], v144 offset:22528
	ds_read_b128 v[214:217], v144 offset:23552
	global_load_lds_dwordx4 v[194:195], off
	s_add_i32 m0, s38, 0x2000
	s_add_u32 s38, s56, 0x40000
	v_lshl_add_u64 v[218:219], s[56:57], 0, v[130:131]
	s_addc_u32 s39, s57, 0
	s_add_i32 s18, s18, s27
	global_load_lds_dwordx4 v[218:219], off
	v_lshl_add_u64 v[220:221], s[38:39], 0, v[0:1]
	s_mov_b32 m0, s18
	v_lshl_add_u64 v[222:223], s[64:65], 0, v[132:133]
	global_load_lds_dwordx4 v[220:221], off
	v_lshl_add_u64 v[220:221], s[38:39], 0, v[130:131]
	s_add_i32 m0, s18, 0x2000
	s_nop 0
	global_load_lds_dwordx4 v[220:221], off
	v_lshl_add_u64 v[220:221], s[64:65], 0, v[134:135]
	s_mov_b32 m0, s29
	s_nop 0
	global_load_lds_dwordx4 v[220:221], off
	s_mov_b32 m0, s33
	s_nop 0
	global_load_lds_dwordx4 v[222:223], off
	s_waitcnt vmcnt(8)
	s_waitcnt lgkmcnt(0)
	s_barrier
; #define PG8_STAGE(bufoff, gbase, voff) do { _Pragma("unroll") for (int _i = 0; _i < 2; ++_i) \
;         __builtin_amdgcn_global_load_lds((const unsigned*)((const char*)(gbase) + (voff)[_i]), (PG8_LAS unsigned*)(lds + (bufoff) + ldsw + _i * 8192), 16, 0, 0); } while (0)
; #define PG8_LDA(dst, b, h) do { _Pragma("unroll") for (int m = 0; m < 4; ++m) _Pragma("unroll") for (int k = 0; k < 2; ++k) dst[m][k] = *(const PG8_LAS bf16x8*)(lds + PG8_SA(b, h) + aoff + m * 2048 + k * 1024); } while (0)
; #define PG8_LDB(dst, b, h) do { _Pragma("unroll") for (int n = 0; n < 2; ++n) _Pragma("unroll") for (int k = 0; k < 2; ++k) dst[n][k] = *(const PG8_LAS bf16x8*)(lds + PG8_SB(b, h) + boff + n * 2048 + k * 1024); } while (0)
; #define PG8_MMA(ai, bj, At, Bt) do { __builtin_amdgcn_s_setprio(1); _Pragma("unroll") for (int m = 0; m < 4; ++m) _Pragma("unroll") for (int n = 0; n < 2; ++n) _Pragma("unroll") for (int k = 0; k < 2; ++k) \
;         acc[ai][bj][m][n] = __builtin_amdgcn_mfma_f32_16x16x32_bf16(Bt[n][k], At[m][k], acc[ai][bj][m][n], 0, 0, 0); __builtin_amdgcn_s_setprio(0); } while (0)
; #define PG8_WAIT_V(n) asm volatile("s_waitcnt vmcnt(" #n ")" ::: "memory")
; #define PG8_WAIT_L(n) asm volatile("s_waitcnt lgkmcnt(" #n ")" ::: "memory")
; #define PG8_BAR __builtin_amdgcn_s_barrier()
; #define PG8_SCHED __builtin_amdgcn_sched_barrier(0)
; template <class Epi, class Sched, bool ALIGN_EPI = false, bool SP2 = false>
; __device__ __forceinline__ void gemm_phase(PG8_LAS unsigned char* lds, const Gemm g, const Sched& S, const Epi& E) {
;     ...
;             PG8_WAIT_V(8); PG8_WAIT_L(0); PG8_BAR; PG8_MMA(1, 0, At, B0); PG8_MMA(1, 1, At, B1); PG8_BAR; PG8_SCHED;
;             PG8_LDB(B0, 1, 0); PG8_LDB(B1, 1, 1); PG8_SCHED; PG8_LDA(At, 1, 0); PG8_STAGE(PG8_SA(0, 1), a2 + hstep, voffA);
;             PG8_WAIT_V(8); PG8_WAIT_L(0); PG8_BAR; PG8_MMA(0, 0, At, B0); PG8_MMA(0, 1, At, B1); PG8_BAR; PG8_SCHED;
	s_setprio 1
	s_waitcnt lgkmcnt(0)
	v_mfma_f32_16x16x32_bf16 v[50:53], v[146:149], v[178:181], v[50:53]
	v_mfma_f32_16x16x32_bf16 v[50:53], v[150:153], v[182:185], v[50:53]
	v_mfma_f32_16x16x32_bf16 v[54:57], v[154:157], v[178:181], v[54:57]
	v_mfma_f32_16x16x32_bf16 v[54:57], v[158:161], v[182:185], v[54:57]
	v_mfma_f32_16x16x32_bf16 v[34:37], v[146:149], v[186:189], v[34:37]
	v_mfma_f32_16x16x32_bf16 v[34:37], v[150:153], v[190:193], v[34:37]
	v_mfma_f32_16x16x32_bf16 v[38:41], v[154:157], v[186:189], v[38:41]
	v_mfma_f32_16x16x32_bf16 v[38:41], v[158:161], v[190:193], v[38:41]
	v_mfma_f32_16x16x32_bf16 v[18:21], v[146:149], v[202:205], v[18:21]
	v_mfma_f32_16x16x32_bf16 v[18:21], v[150:153], v[206:209], v[18:21]
	v_mfma_f32_16x16x32_bf16 v[22:25], v[154:157], v[202:205], v[22:25]
	v_mfma_f32_16x16x32_bf16 v[22:25], v[158:161], v[206:209], v[22:25]
	v_mfma_f32_16x16x32_bf16 v[2:5], v[146:149], v[210:213], v[2:5]
	v_mfma_f32_16x16x32_bf16 v[2:5], v[150:153], v[214:217], v[2:5]
	v_mfma_f32_16x16x32_bf16 v[6:9], v[154:157], v[210:213], v[6:9]
	v_mfma_f32_16x16x32_bf16 v[6:9], v[158:161], v[214:217], v[6:9]
	s_setprio 0
	s_setprio 1
	v_mfma_f32_16x16x32_bf16 v[58:61], v[162:165], v[178:181], v[58:61]
	v_mfma_f32_16x16x32_bf16 v[58:61], v[166:169], v[182:185], v[58:61]
	v_mfma_f32_16x16x32_bf16 v[62:65], v[170:173], v[178:181], v[62:65]
	v_mfma_f32_16x16x32_bf16 v[62:65], v[174:177], v[182:185], v[62:65]
	v_mfma_f32_16x16x32_bf16 v[42:45], v[162:165], v[186:189], v[42:45]
	v_mfma_f32_16x16x32_bf16 v[42:45], v[166:169], v[190:193], v[42:45]
	v_mfma_f32_16x16x32_bf16 v[46:49], v[170:173], v[186:189], v[46:49]
	v_mfma_f32_16x16x32_bf16 v[46:49], v[174:177], v[190:193], v[46:49]
	v_mfma_f32_16x16x32_bf16 v[26:29], v[162:165], v[202:205], v[26:29]
	v_mfma_f32_16x16x32_bf16 v[26:29], v[166:169], v[206:209], v[26:29]
	v_mfma_f32_16x16x32_bf16 v[30:33], v[170:173], v[202:205], v[30:33]
	v_mfma_f32_16x16x32_bf16 v[30:33], v[174:177], v[206:209], v[30:33]
	v_mfma_f32_16x16x32_bf16 v[10:13], v[162:165], v[210:213], v[10:13]
	v_mfma_f32_16x16x32_bf16 v[10:13], v[166:169], v[214:217], v[10:13]
	v_mfma_f32_16x16x32_bf16 v[14:17], v[170:173], v[210:213], v[14:17]
	v_mfma_f32_16x16x32_bf16 v[14:17], v[174:177], v[214:217], v[14:17]
	s_setprio 0
	s_barrier
	s_add_i32 s18, 0, 0x18000
	v_add_u32_e32 v145, s18, v141
	s_add_i32 s83, 0, 0x1c000
	ds_read_b128 v[146:149], v145
	ds_read_b128 v[150:153], v145 offset:1024
	ds_read_b128 v[154:157], v145 offset:2048
	ds_read_b128 v[158:161], v145 offset:3072
	v_add_u32_e32 v145, s83, v141
	ds_read_b128 v[162:165], v145
	ds_read_b128 v[166:169], v145 offset:1024
	ds_read_b128 v[170:173], v145 offset:2048
	ds_read_b128 v[174:177], v145 offset:3072
	s_add_u32 s38, s64, 0x40000
	s_addc_u32 s39, s65, 0
	s_mov_b32 m0, s58
	v_lshl_add_u64 v[224:225], s[38:39], 0, v[134:135]
	ds_read_b128 v[178:181], v144 offset:32768
	ds_read_b128 v[182:185], v144 offset:33792
	ds_read_b128 v[186:189], v144 offset:34816
	ds_read_b128 v[190:193], v144 offset:35840
	ds_read_b128 v[202:205], v144 offset:36864
	ds_read_b128 v[206:209], v144 offset:37888
	ds_read_b128 v[210:213], v144 offset:38912
	ds_read_b128 v[214:217], v144 offset:39936
	global_load_lds_dwordx4 v[224:225], off
	v_lshl_add_u64 v[224:225], s[38:39], 0, v[132:133]
	s_mov_b32 m0, s69
	s_nop 0
	global_load_lds_dwordx4 v[224:225], off
	s_waitcnt vmcnt(8)
	s_waitcnt lgkmcnt(0)
	s_barrier
	s_setprio 1
	s_waitcnt lgkmcnt(0)
	v_mfma_f32_16x16x32_bf16 v[114:117], v[146:149], v[178:181], v[114:117]
	v_mfma_f32_16x16x32_bf16 v[114:117], v[150:153], v[182:185], v[114:117]
	v_mfma_f32_16x16x32_bf16 v[118:121], v[154:157], v[178:181], v[118:121]
	v_mfma_f32_16x16x32_bf16 v[118:121], v[158:161], v[182:185], v[118:121]
	v_mfma_f32_16x16x32_bf16 v[98:101], v[146:149], v[186:189], v[98:101]
	v_mfma_f32_16x16x32_bf16 v[98:101], v[150:153], v[190:193], v[98:101]
	v_mfma_f32_16x16x32_bf16 v[102:105], v[154:157], v[186:189], v[102:105]
	v_mfma_f32_16x16x32_bf16 v[102:105], v[158:161], v[190:193], v[102:105]
	v_mfma_f32_16x16x32_bf16 v[82:85], v[146:149], v[202:205], v[82:85]
	v_mfma_f32_16x16x32_bf16 v[82:85], v[150:153], v[206:209], v[82:85]
	v_mfma_f32_16x16x32_bf16 v[86:89], v[154:157], v[202:205], v[86:89]
	v_mfma_f32_16x16x32_bf16 v[86:89], v[158:161], v[206:209], v[86:89]
	v_mfma_f32_16x16x32_bf16 v[66:69], v[146:149], v[210:213], v[66:69]
	v_mfma_f32_16x16x32_bf16 v[66:69], v[150:153], v[214:217], v[66:69]
	v_mfma_f32_16x16x32_bf16 v[70:73], v[154:157], v[210:213], v[70:73]
	v_mfma_f32_16x16x32_bf16 v[70:73], v[158:161], v[214:217], v[70:73]
	s_setprio 0
	s_setprio 1
	v_mfma_f32_16x16x32_bf16 v[122:125], v[162:165], v[178:181], v[122:125]
	v_mfma_f32_16x16x32_bf16 v[122:125], v[166:169], v[182:185], v[122:125]
	v_mfma_f32_16x16x32_bf16 v[126:129], v[170:173], v[178:181], v[126:129]
	v_mfma_f32_16x16x32_bf16 v[126:129], v[174:177], v[182:185], v[126:129]
	v_mfma_f32_16x16x32_bf16 v[106:109], v[162:165], v[186:189], v[106:109]
	v_mfma_f32_16x16x32_bf16 v[106:109], v[166:169], v[190:193], v[106:109]
	v_mfma_f32_16x16x32_bf16 v[110:113], v[170:173], v[186:189], v[110:113]
	v_mfma_f32_16x16x32_bf16 v[110:113], v[174:177], v[190:193], v[110:113]
	v_mfma_f32_16x16x32_bf16 v[90:93], v[162:165], v[202:205], v[90:93]
	v_mfma_f32_16x16x32_bf16 v[90:93], v[166:169], v[206:209], v[90:93]
	v_mfma_f32_16x16x32_bf16 v[94:97], v[170:173], v[202:205], v[94:97]
	v_mfma_f32_16x16x32_bf16 v[94:97], v[174:177], v[206:209], v[94:97]
	v_mfma_f32_16x16x32_bf16 v[74:77], v[162:165], v[210:213], v[74:77]
	v_mfma_f32_16x16x32_bf16 v[74:77], v[166:169], v[214:217], v[74:77]
	v_mfma_f32_16x16x32_bf16 v[78:81], v[170:173], v[210:213], v[78:81]
	v_mfma_f32_16x16x32_bf16 v[78:81], v[174:177], v[214:217], v[78:81]
	s_setprio 0
	s_barrier
; #define PG8_STAGE(bufoff, gbase, voff) do { _Pragma("unroll") for (int _i = 0; _i < 2; ++_i) \
;         __builtin_amdgcn_global_load_lds((const unsigned*)((const char*)(gbase) + (voff)[_i]), (PG8_LAS unsigned*)(lds + (bufoff) + ldsw + _i * 8192), 16, 0, 0); } while (0)
; #define PG8_LDA(dst, b, h) do { _Pragma("unroll") for (int m = 0; m < 4; ++m) _Pragma("unroll") for (int k = 0; k < 2; ++k) dst[m][k] = *(const PG8_LAS bf16x8*)(lds + PG8_SA(b, h) + aoff + m * 2048 + k * 1024); } while (0)
; #define PG8_MMA(ai, bj, At, Bt) do { __builtin_amdgcn_s_setprio(1); _Pragma("unroll") for (int m = 0; m < 4; ++m) _Pragma("unroll") for (int n = 0; n < 2; ++n) _Pragma("unroll") for (int k = 0; k < 2; ++k) \
;         acc[ai][bj][m][n] = __builtin_amdgcn_mfma_f32_16x16x32_bf16(Bt[n][k], At[m][k], acc[ai][bj][m][n], 0, 0, 0); __builtin_amdgcn_s_setprio(0); } while (0)
; #define PG8_WAIT_V(n) asm volatile("s_waitcnt vmcnt(" #n ")" ::: "memory")
; #define PG8_WAIT_L(n) asm volatile("s_waitcnt lgkmcnt(" #n ")" ::: "memory")
; #define PG8_BAR __builtin_amdgcn_s_barrier()
; #define PG8_SCHED __builtin_amdgcn_sched_barrier(0)
; template <class Epi, class Sched, bool ALIGN_EPI = false, bool SP2 = false>
; __device__ __forceinline__ void gemm_phase(PG8_LAS unsigned char* lds, const Gemm g, const Sched& S, const Epi& E) {
;     ...
;         for (int t = 0; t < nt; t += 2) {
;             const bool last = (t == nt - 2);
;             const char* a1 = cA + (size_t)(t + 1) * kstep;
;             const char* a2 = last ? nA : cA + (size_t)(t + 2) * kstep; const char* b2 = last ? nB : cB + (size_t)(t + 2) * kstep;
;             const char* a3 = a2 + kstep; const char* b3 = b2 + kstep;
;             if (last && has_next) S.a_ready(nxt);
;     ...
;             PG8_LDA(At, 1, 1); PG8_STAGE(PG8_SB(1, 0), b3, voffB); PG8_STAGE(PG8_SB(1, 1), b3 + hstep, voffB); PG8_STAGE(PG8_SA(1, 0), a3, voffA);
;             PG8_WAIT_V(8); PG8_WAIT_L(0); PG8_BAR; PG8_MMA(1, 0, At, B0); PG8_MMA(1, 1, At, B1); PG8_BAR; PG8_SCHED;
	s_add_i32 s18, s18, s27
	v_lshl_add_u64 v[194:195], v[194:195], 0, s[30:31]
	s_mov_b32 m0, s18
	ds_read_b128 v[178:181], v144 offset:49152
	ds_read_b128 v[182:185], v144 offset:50176
	ds_read_b128 v[186:189], v144 offset:51200
	ds_read_b128 v[190:193], v144 offset:52224
	ds_read_b128 v[202:205], v144 offset:53248
	ds_read_b128 v[206:209], v144 offset:54272
	ds_read_b128 v[210:213], v144 offset:55296
	ds_read_b128 v[214:217], v144 offset:56320
	global_load_lds_dwordx4 v[194:195], off
	s_add_i32 m0, s18, 0x2000
	s_add_u32 s38, s56, 0x40080
	v_lshl_add_u64 v[194:195], v[218:219], 0, s[30:31]
	s_addc_u32 s39, s57, 0
	s_add_i32 s18, s83, s27
	global_load_lds_dwordx4 v[194:195], off
	v_lshl_add_u64 v[194:195], s[38:39], 0, v[0:1]
	s_mov_b32 m0, s18
	s_nop 0
	global_load_lds_dwordx4 v[194:195], off
	v_lshl_add_u64 v[194:195], s[38:39], 0, v[130:131]
	s_add_i32 m0, s18, 0x2000
	s_nop 0
	global_load_lds_dwordx4 v[194:195], off
	v_lshl_add_u64 v[194:195], v[220:221], 0, s[30:31]
	s_mov_b32 m0, s71
	s_nop 0
	global_load_lds_dwordx4 v[194:195], off
	v_lshl_add_u64 v[194:195], v[222:223], 0, s[30:31]
	s_mov_b32 m0, s72
	s_nop 0
	global_load_lds_dwordx4 v[194:195], off
	s_waitcnt vmcnt(8)
	s_waitcnt lgkmcnt(0)
	s_barrier
	s_setprio 1
	s_waitcnt lgkmcnt(0)
	v_mfma_f32_16x16x32_bf16 v[50:53], v[146:149], v[178:181], v[50:53]
	v_mfma_f32_16x16x32_bf16 v[50:53], v[150:153], v[182:185], v[50:53]
	v_mfma_f32_16x16x32_bf16 v[54:57], v[154:157], v[178:181], v[54:57]
	v_mfma_f32_16x16x32_bf16 v[54:57], v[158:161], v[182:185], v[54:57]
	v_mfma_f32_16x16x32_bf16 v[34:37], v[146:149], v[186:189], v[34:37]
	v_mfma_f32_16x16x32_bf16 v[34:37], v[150:153], v[190:193], v[34:37]
	v_mfma_f32_16x16x32_bf16 v[38:41], v[154:157], v[186:189], v[38:41]
	v_mfma_f32_16x16x32_bf16 v[38:41], v[158:161], v[190:193], v[38:41]
	v_mfma_f32_16x16x32_bf16 v[18:21], v[146:149], v[202:205], v[18:21]
	v_mfma_f32_16x16x32_bf16 v[18:21], v[150:153], v[206:209], v[18:21]
	v_mfma_f32_16x16x32_bf16 v[22:25], v[154:157], v[202:205], v[22:25]
	v_mfma_f32_16x16x32_bf16 v[22:25], v[158:161], v[206:209], v[22:25]
	v_mfma_f32_16x16x32_bf16 v[2:5], v[146:149], v[210:213], v[2:5]
	v_mfma_f32_16x16x32_bf16 v[2:5], v[150:153], v[214:217], v[2:5]
	v_mfma_f32_16x16x32_bf16 v[6:9], v[154:157], v[210:213], v[6:9]
	v_mfma_f32_16x16x32_bf16 v[6:9], v[158:161], v[214:217], v[6:9]
	s_setprio 0
	s_setprio 1
	v_mfma_f32_16x16x32_bf16 v[58:61], v[162:165], v[178:181], v[58:61]
	v_mfma_f32_16x16x32_bf16 v[58:61], v[166:169], v[182:185], v[58:61]
	v_mfma_f32_16x16x32_bf16 v[62:65], v[170:173], v[178:181], v[62:65]
	v_mfma_f32_16x16x32_bf16 v[62:65], v[174:177], v[182:185], v[62:65]
	v_mfma_f32_16x16x32_bf16 v[42:45], v[162:165], v[186:189], v[42:45]
	v_mfma_f32_16x16x32_bf16 v[42:45], v[166:169], v[190:193], v[42:45]
	v_mfma_f32_16x16x32_bf16 v[46:49], v[170:173], v[186:189], v[46:49]
	v_mfma_f32_16x16x32_bf16 v[46:49], v[174:177], v[190:193], v[46:49]
	v_mfma_f32_16x16x32_bf16 v[26:29], v[162:165], v[202:205], v[26:29]
	v_mfma_f32_16x16x32_bf16 v[26:29], v[166:169], v[206:209], v[26:29]
	v_mfma_f32_16x16x32_bf16 v[30:33], v[170:173], v[202:205], v[30:33]
	v_mfma_f32_16x16x32_bf16 v[30:33], v[174:177], v[206:209], v[30:33]
	v_mfma_f32_16x16x32_bf16 v[10:13], v[162:165], v[210:213], v[10:13]
	v_mfma_f32_16x16x32_bf16 v[10:13], v[166:169], v[214:217], v[10:13]
	v_mfma_f32_16x16x32_bf16 v[14:17], v[170:173], v[210:213], v[14:17]
	v_mfma_f32_16x16x32_bf16 v[14:17], v[174:177], v[214:217], v[14:17]
	s_setprio 0
	s_barrier
	s_add_i32 s82, s82, 2
	s_add_u32 s60, s60, 0x100
	s_addc_u32 s61, s61, 0
	s_add_u32 s80, s80, 0x100
	s_addc_u32 s81, s81, 0
	s_cmp_gt_u32 s82, 13
	s_cbranch_scc0 .LBB0_220
	s_and_b64 vcc, exec, s[44:45]
	s_cbranch_vccz .LBB0_223
	s_barrier

; #define PG8_STAGE(bufoff, gbase, voff) do { _Pragma("unroll") for (int _i = 0; _i < 2; ++_i) \
;         __builtin_amdgcn_global_load_lds((const unsigned*)((const char*)(gbase) + (voff)[_i]), (PG8_LAS unsigned*)(lds + (bufoff) + ldsw + _i * 8192), 16, 0, 0); } while (0)
; #define PG8_LDA(dst, b, h) do { _Pragma("unroll") for (int m = 0; m < 4; ++m) _Pragma("unroll") for (int k = 0; k < 2; ++k) dst[m][k] = *(const PG8_LAS bf16x8*)(lds + PG8_SA(b, h) + aoff + m * 2048 + k * 1024); } while (0)
; #define PG8_LDB(dst, b, h) do { _Pragma("unroll") for (int n = 0; n < 2; ++n) _Pragma("unroll") for (int k = 0; k < 2; ++k) dst[n][k] = *(const PG8_LAS bf16x8*)(lds + PG8_SB(b, h) + boff + n * 2048 + k * 1024); } while (0)
; #define PG8_MMA(ai, bj, At, Bt) do { __builtin_amdgcn_s_setprio(1); _Pragma("unroll") for (int m = 0; m < 4; ++m) _Pragma("unroll") for (int n = 0; n < 2; ++n) _Pragma("unroll") for (int k = 0; k < 2; ++k) \
;         acc[ai][bj][m][n] = __builtin_amdgcn_mfma_f32_16x16x32_bf16(Bt[n][k], At[m][k], acc[ai][bj][m][n], 0, 0, 0); __builtin_amdgcn_s_setprio(0); } while (0)
; #define PG8_WAIT_V(n) asm volatile("s_waitcnt vmcnt(" #n ")" ::: "memory")
; #define PG8_WAIT_L(n) asm volatile("s_waitcnt lgkmcnt(" #n ")" ::: "memory")
; template <class Epi, class Sched, bool ALIGN_EPI = false, bool SP2 = false>
; __device__ __forceinline__ void gemm_phase(PG8_LAS unsigned char* lds, const Gemm g, const Sched& S, const Epi& E) {
;     ...
;             const bool last = (t == nt - 2);
;             const char* a1 = cA + (size_t)(t + 1) * kstep;
;             const char* a2 = last ? nA : cA + (size_t)(t + 2) * kstep; const char* b2 = last ? nB : cB + (size_t)(t + 2) * kstep;
;             const char* a3 = a2 + kstep; const char* b3 = b2 + kstep;
;             if (last && has_next) S.a_ready(nxt);
;             if constexpr (SP2) {
;             PG8_LDB(B0, 0, 0); PG8_LDB(B1, 0, 1); PG8_SCHED; PG8_LDA(At, 0, 0); PG8_STAGE(PG8_SA(1, 1), a1 + hstep, voffA);
;             PG8_WAIT_V(8); PG8_WAIT_L(0); PG8_BAR; PG8_MMA(0, 0, At, B0); PG8_MMA(0, 1, At, B1); PG8_BAR; PG8_SCHED;
;             PG8_LDA(At, 0, 1); PG8_STAGE(PG8_SB(0, 0), b2, voffB); PG8_STAGE(PG8_SB(0, 1), b2 + hstep, voffB); PG8_STAGE(PG8_SA(0, 0), a2, voffA);
;             PG8_WAIT_V(8); PG8_WAIT_L(0); PG8_BAR; PG8_MMA(1, 0, At, B0); PG8_MMA(1, 1, At, B1); PG8_BAR; PG8_SCHED;
.LBB0_274:
	s_add_i32 vcc_lo, s46, 2
	s_add_u32 s38, s48, 0x80
	s_addc_u32 s39, s49, 0
	s_add_i32 vcc_hi, 0, 0x10000
	s_cmp_eq_u32 s99, s46
	s_cselect_b32 s47, s81, s39
	s_cselect_b32 s46, s80, s38
	s_cselect_b32 s39, s83, s51
	s_cselect_b32 s38, s82, s50
	s_add_i32 s18, 0, 0x14000
	v_add_u32_e32 v142, vcc_hi, v245
	v_add_u32_e32 v158, s18, v245
	ds_read_b128 v[110:113], v142
	ds_read_b128 v[118:121], v142 offset:1024
	ds_read_b128 v[138:141], v142 offset:2048
	ds_read_b128 v[142:145], v142 offset:3072
	ds_read_b128 v[146:149], v158
	ds_read_b128 v[150:153], v158 offset:1024
	ds_read_b128 v[154:157], v158 offset:2048
	ds_read_b128 v[158:161], v158 offset:3072
	v_lshl_add_u64 v[210:211], s[48:49], 0, v[206:207]
	s_add_i32 m0, s92, 0xc000
	ds_read_b128 v[162:165], v247
	ds_read_b128 v[166:169], v247 offset:1024
	ds_read_b128 v[170:173], v247 offset:2048
	ds_read_b128 v[174:177], v247 offset:3072
	ds_read_b128 v[178:181], v247 offset:4096
	ds_read_b128 v[182:185], v247 offset:5120
	ds_read_b128 v[186:189], v247 offset:6144
	ds_read_b128 v[190:193], v247 offset:7168
	global_load_lds_dwordx4 v[210:211], off
	v_lshl_add_u64 v[210:211], s[48:49], 0, v[208:209]
	s_add_i32 m0, s92, 0xe000
	s_nop 0
	global_load_lds_dwordx4 v[210:211], off
	s_waitcnt vmcnt(8)
	s_waitcnt lgkmcnt(0)
	s_barrier
	s_setprio 1
	s_waitcnt lgkmcnt(0)
	v_mfma_f32_16x16x32_bf16 v[130:133], v[110:113], v[162:165], v[130:133]
	v_mfma_f32_16x16x32_bf16 v[130:133], v[118:121], v[166:169], v[130:133]
	v_mfma_f32_16x16x32_bf16 v[134:137], v[138:141], v[162:165], v[134:137]
	v_mfma_f32_16x16x32_bf16 v[134:137], v[142:145], v[166:169], v[134:137]
	v_mfma_f32_16x16x32_bf16 v[114:117], v[110:113], v[170:173], v[114:117]
	v_mfma_f32_16x16x32_bf16 v[114:117], v[118:121], v[174:177], v[114:117]
	v_mfma_f32_16x16x32_bf16 v[106:109], v[138:141], v[170:173], v[106:109]
	v_mfma_f32_16x16x32_bf16 v[106:109], v[142:145], v[174:177], v[106:109]
	v_mfma_f32_16x16x32_bf16 v[94:97], v[110:113], v[178:181], v[94:97]
	v_mfma_f32_16x16x32_bf16 v[94:97], v[118:121], v[182:185], v[94:97]
	v_mfma_f32_16x16x32_bf16 v[90:93], v[138:141], v[178:181], v[90:93]
	v_mfma_f32_16x16x32_bf16 v[90:93], v[142:145], v[182:185], v[90:93]
	v_mfma_f32_16x16x32_bf16 v[78:81], v[110:113], v[186:189], v[78:81]
	v_mfma_f32_16x16x32_bf16 v[78:81], v[118:121], v[190:193], v[78:81]
	v_mfma_f32_16x16x32_bf16 v[74:77], v[138:141], v[186:189], v[74:77]
	v_mfma_f32_16x16x32_bf16 v[74:77], v[142:145], v[190:193], v[74:77]
	s_setprio 0
	s_setprio 1
	v_mfma_f32_16x16x32_bf16 v[126:129], v[146:149], v[162:165], v[126:129]
	v_mfma_f32_16x16x32_bf16 v[126:129], v[150:153], v[166:169], v[126:129]
	v_mfma_f32_16x16x32_bf16 v[122:125], v[154:157], v[162:165], v[122:125]
	v_mfma_f32_16x16x32_bf16 v[122:125], v[158:161], v[166:169], v[122:125]
	v_mfma_f32_16x16x32_bf16 v[102:105], v[146:149], v[170:173], v[102:105]
	v_mfma_f32_16x16x32_bf16 v[102:105], v[150:153], v[174:177], v[102:105]
	v_mfma_f32_16x16x32_bf16 v[98:101], v[154:157], v[170:173], v[98:101]
	v_mfma_f32_16x16x32_bf16 v[98:101], v[158:161], v[174:177], v[98:101]
	v_mfma_f32_16x16x32_bf16 v[86:89], v[146:149], v[178:181], v[86:89]
	v_mfma_f32_16x16x32_bf16 v[86:89], v[150:153], v[182:185], v[86:89]
	v_mfma_f32_16x16x32_bf16 v[82:85], v[154:157], v[178:181], v[82:85]
	v_mfma_f32_16x16x32_bf16 v[82:85], v[158:161], v[182:185], v[82:85]
	v_mfma_f32_16x16x32_bf16 v[70:73], v[146:149], v[186:189], v[70:73]
	v_mfma_f32_16x16x32_bf16 v[70:73], v[150:153], v[190:193], v[70:73]
	v_mfma_f32_16x16x32_bf16 v[66:69], v[154:157], v[186:189], v[66:69]
	v_mfma_f32_16x16x32_bf16 v[66:69], v[158:161], v[190:193], v[66:69]
	s_setprio 0
	s_barrier
	s_add_i32 vcc_hi, vcc_hi, s6
	v_lshl_add_u64 v[210:211], s[38:39], 0, v[0:1]
	s_mov_b32 m0, vcc_hi
	ds_read_b128 v[162:165], v247 offset:16384
	ds_read_b128 v[166:169], v247 offset:17408
	ds_read_b128 v[170:173], v247 offset:18432
	ds_read_b128 v[174:177], v247 offset:19456
	ds_read_b128 v[178:181], v247 offset:20480
	ds_read_b128 v[182:185], v247 offset:21504
	ds_read_b128 v[186:189], v247 offset:22528
	ds_read_b128 v[190:193], v247 offset:23552
	global_load_lds_dwordx4 v[210:211], off
	s_add_i32 m0, vcc_hi, 0x2000
	v_lshl_add_u64 v[212:213], s[38:39], 0, v[204:205]
	s_add_u32 s38, s38, s58
	s_addc_u32 s39, s39, 0
	s_add_i32 s18, s18, s6
	global_load_lds_dwordx4 v[212:213], off
	v_lshl_add_u64 v[214:215], s[38:39], 0, v[0:1]
	s_mov_b32 m0, s18
	v_lshl_add_u64 v[216:217], s[38:39], 0, v[204:205]
	global_load_lds_dwordx4 v[214:215], off
	s_add_i32 m0, s18, 0x2000
	v_lshl_add_u64 v[218:219], s[46:47], 0, v[194:195]
	global_load_lds_dwordx4 v[216:217], off
	s_mov_b32 m0, s92
	v_lshl_add_u64 v[220:221], s[46:47], 0, v[202:203]
	global_load_lds_dwordx4 v[218:219], off
	s_mov_b32 m0, s93
	s_nop 0
	global_load_lds_dwordx4 v[220:221], off
	s_waitcnt vmcnt(8)
	s_waitcnt lgkmcnt(0)
	s_barrier
; #define PG8_STAGE(bufoff, gbase, voff) do { _Pragma("unroll") for (int _i = 0; _i < 2; ++_i) \
;         __builtin_amdgcn_global_load_lds((const unsigned*)((const char*)(gbase) + (voff)[_i]), (PG8_LAS unsigned*)(lds + (bufoff) + ldsw + _i * 8192), 16, 0, 0); } while (0)
; #define PG8_LDA(dst, b, h) do { _Pragma("unroll") for (int m = 0; m < 4; ++m) _Pragma("unroll") for (int k = 0; k < 2; ++k) dst[m][k] = *(const PG8_LAS bf16x8*)(lds + PG8_SA(b, h) + aoff + m * 2048 + k * 1024); } while (0)
; #define PG8_LDB(dst, b, h) do { _Pragma("unroll") for (int n = 0; n < 2; ++n) _Pragma("unroll") for (int k = 0; k < 2; ++k) dst[n][k] = *(const PG8_LAS bf16x8*)(lds + PG8_SB(b, h) + boff + n * 2048 + k * 1024); } while (0)
; #define PG8_MMA(ai, bj, At, Bt) do { __builtin_amdgcn_s_setprio(1); _Pragma("unroll") for (int m = 0; m < 4; ++m) _Pragma("unroll") for (int n = 0; n < 2; ++n) _Pragma("unroll") for (int k = 0; k < 2; ++k) \
;         acc[ai][bj][m][n] = __builtin_amdgcn_mfma_f32_16x16x32_bf16(Bt[n][k], At[m][k], acc[ai][bj][m][n], 0, 0, 0); __builtin_amdgcn_s_setprio(0); } while (0)
; #define PG8_WAIT_V(n) asm volatile("s_waitcnt vmcnt(" #n ")" ::: "memory")
; #define PG8_WAIT_L(n) asm volatile("s_waitcnt lgkmcnt(" #n ")" ::: "memory")
; #define PG8_BAR __builtin_amdgcn_s_barrier()
; #define PG8_SCHED __builtin_amdgcn_sched_barrier(0)
; template <class Epi, class Sched, bool ALIGN_EPI = false, bool SP2 = false>
; __device__ __forceinline__ void gemm_phase(PG8_LAS unsigned char* lds, const Gemm g, const Sched& S, const Epi& E) {
;     ...
;             PG8_WAIT_V(8); PG8_WAIT_L(0); PG8_BAR; PG8_MMA(1, 0, At, B0); PG8_MMA(1, 1, At, B1); PG8_BAR; PG8_SCHED;
;             PG8_LDB(B0, 1, 0); PG8_LDB(B1, 1, 1); PG8_SCHED; PG8_LDA(At, 1, 0); PG8_STAGE(PG8_SA(0, 1), a2 + hstep, voffA);
;             PG8_WAIT_V(8); PG8_WAIT_L(0); PG8_BAR; PG8_MMA(0, 0, At, B0); PG8_MMA(0, 1, At, B1); PG8_BAR; PG8_SCHED;
	s_setprio 1
	s_waitcnt lgkmcnt(0)
	v_mfma_f32_16x16x32_bf16 v[62:65], v[110:113], v[162:165], v[62:65]
	v_mfma_f32_16x16x32_bf16 v[62:65], v[118:121], v[166:169], v[62:65]
	v_mfma_f32_16x16x32_bf16 v[58:61], v[138:141], v[162:165], v[58:61]
	v_mfma_f32_16x16x32_bf16 v[58:61], v[142:145], v[166:169], v[58:61]
	v_mfma_f32_16x16x32_bf16 v[46:49], v[110:113], v[170:173], v[46:49]
	v_mfma_f32_16x16x32_bf16 v[46:49], v[118:121], v[174:177], v[46:49]
	v_mfma_f32_16x16x32_bf16 v[42:45], v[138:141], v[170:173], v[42:45]
	v_mfma_f32_16x16x32_bf16 v[42:45], v[142:145], v[174:177], v[42:45]
	v_mfma_f32_16x16x32_bf16 v[30:33], v[110:113], v[178:181], v[30:33]
	v_mfma_f32_16x16x32_bf16 v[30:33], v[118:121], v[182:185], v[30:33]
	v_mfma_f32_16x16x32_bf16 v[26:29], v[138:141], v[178:181], v[26:29]
	v_mfma_f32_16x16x32_bf16 v[26:29], v[142:145], v[182:185], v[26:29]
	v_mfma_f32_16x16x32_bf16 v[14:17], v[110:113], v[186:189], v[14:17]
	v_mfma_f32_16x16x32_bf16 v[14:17], v[118:121], v[190:193], v[14:17]
	v_mfma_f32_16x16x32_bf16 v[10:13], v[138:141], v[186:189], v[10:13]
	v_mfma_f32_16x16x32_bf16 v[10:13], v[142:145], v[190:193], v[10:13]
	s_setprio 0
	s_setprio 1
	v_mfma_f32_16x16x32_bf16 v[54:57], v[146:149], v[162:165], v[54:57]
	v_mfma_f32_16x16x32_bf16 v[54:57], v[150:153], v[166:169], v[54:57]
	v_mfma_f32_16x16x32_bf16 v[50:53], v[154:157], v[162:165], v[50:53]
	v_mfma_f32_16x16x32_bf16 v[50:53], v[158:161], v[166:169], v[50:53]
	v_mfma_f32_16x16x32_bf16 v[38:41], v[146:149], v[170:173], v[38:41]
	v_mfma_f32_16x16x32_bf16 v[38:41], v[150:153], v[174:177], v[38:41]
	v_mfma_f32_16x16x32_bf16 v[34:37], v[154:157], v[170:173], v[34:37]
	v_mfma_f32_16x16x32_bf16 v[34:37], v[158:161], v[174:177], v[34:37]
	v_mfma_f32_16x16x32_bf16 v[22:25], v[146:149], v[178:181], v[22:25]
	v_mfma_f32_16x16x32_bf16 v[22:25], v[150:153], v[182:185], v[22:25]
	v_mfma_f32_16x16x32_bf16 v[18:21], v[154:157], v[178:181], v[18:21]
	v_mfma_f32_16x16x32_bf16 v[18:21], v[158:161], v[182:185], v[18:21]
	v_mfma_f32_16x16x32_bf16 v[6:9], v[146:149], v[186:189], v[6:9]
	v_mfma_f32_16x16x32_bf16 v[6:9], v[150:153], v[190:193], v[6:9]
	v_mfma_f32_16x16x32_bf16 v[2:5], v[154:157], v[186:189], v[2:5]
	v_mfma_f32_16x16x32_bf16 v[2:5], v[158:161], v[190:193], v[2:5]
	s_setprio 0
	s_barrier
	s_add_i32 s18, 0, 0x18000
	s_add_i32 vcc_hi, 0, 0x1c000
	v_add_u32_e32 v142, s18, v245
	v_add_u32_e32 v158, vcc_hi, v245
	ds_read_b128 v[110:113], v142
	ds_read_b128 v[118:121], v142 offset:1024
	ds_read_b128 v[138:141], v142 offset:2048
	ds_read_b128 v[142:145], v142 offset:3072
	ds_read_b128 v[146:149], v158
	ds_read_b128 v[150:153], v158 offset:1024
	ds_read_b128 v[154:157], v158 offset:2048
	ds_read_b128 v[158:161], v158 offset:3072
	s_add_u32 s38, s46, s58
	s_addc_u32 s39, s47, 0
	s_mov_b32 m0, s94
	v_lshl_add_u64 v[222:223], s[38:39], 0, v[194:195]
	ds_read_b128 v[162:165], v247 offset:32768
	ds_read_b128 v[166:169], v247 offset:33792
	ds_read_b128 v[170:173], v247 offset:34816
	ds_read_b128 v[174:177], v247 offset:35840
	ds_read_b128 v[178:181], v247 offset:36864
	ds_read_b128 v[182:185], v247 offset:37888
	ds_read_b128 v[186:189], v247 offset:38912
	ds_read_b128 v[190:193], v247 offset:39936
	global_load_lds_dwordx4 v[222:223], off
	v_lshl_add_u64 v[222:223], s[38:39], 0, v[202:203]
	s_mov_b32 m0, s95
	s_nop 0
	global_load_lds_dwordx4 v[222:223], off
	s_waitcnt vmcnt(8)
	s_waitcnt lgkmcnt(0)
	s_barrier
	s_setprio 1
	s_waitcnt lgkmcnt(0)
	v_mfma_f32_16x16x32_bf16 v[130:133], v[110:113], v[162:165], v[130:133]
	v_mfma_f32_16x16x32_bf16 v[130:133], v[118:121], v[166:169], v[130:133]
	v_mfma_f32_16x16x32_bf16 v[134:137], v[138:141], v[162:165], v[134:137]
	v_mfma_f32_16x16x32_bf16 v[134:137], v[142:145], v[166:169], v[134:137]
	v_mfma_f32_16x16x32_bf16 v[114:117], v[110:113], v[170:173], v[114:117]
	v_mfma_f32_16x16x32_bf16 v[114:117], v[118:121], v[174:177], v[114:117]
	v_mfma_f32_16x16x32_bf16 v[106:109], v[138:141], v[170:173], v[106:109]
	v_mfma_f32_16x16x32_bf16 v[106:109], v[142:145], v[174:177], v[106:109]
	v_mfma_f32_16x16x32_bf16 v[94:97], v[110:113], v[178:181], v[94:97]
	v_mfma_f32_16x16x32_bf16 v[94:97], v[118:121], v[182:185], v[94:97]
	v_mfma_f32_16x16x32_bf16 v[90:93], v[138:141], v[178:181], v[90:93]
	v_mfma_f32_16x16x32_bf16 v[90:93], v[142:145], v[182:185], v[90:93]
	v_mfma_f32_16x16x32_bf16 v[78:81], v[110:113], v[186:189], v[78:81]
	v_mfma_f32_16x16x32_bf16 v[78:81], v[118:121], v[190:193], v[78:81]
	v_mfma_f32_16x16x32_bf16 v[74:77], v[138:141], v[186:189], v[74:77]
	v_mfma_f32_16x16x32_bf16 v[74:77], v[142:145], v[190:193], v[74:77]
	s_setprio 0
	s_setprio 1
	v_mfma_f32_16x16x32_bf16 v[126:129], v[146:149], v[162:165], v[126:129]
	v_mfma_f32_16x16x32_bf16 v[126:129], v[150:153], v[166:169], v[126:129]
	v_mfma_f32_16x16x32_bf16 v[122:125], v[154:157], v[162:165], v[122:125]
	v_mfma_f32_16x16x32_bf16 v[122:125], v[158:161], v[166:169], v[122:125]
	v_mfma_f32_16x16x32_bf16 v[102:105], v[146:149], v[170:173], v[102:105]
	v_mfma_f32_16x16x32_bf16 v[102:105], v[150:153], v[174:177], v[102:105]
	v_mfma_f32_16x16x32_bf16 v[98:101], v[154:157], v[170:173], v[98:101]
	v_mfma_f32_16x16x32_bf16 v[98:101], v[158:161], v[174:177], v[98:101]
	v_mfma_f32_16x16x32_bf16 v[86:89], v[146:149], v[178:181], v[86:89]
	v_mfma_f32_16x16x32_bf16 v[86:89], v[150:153], v[182:185], v[86:89]
	v_mfma_f32_16x16x32_bf16 v[82:85], v[154:157], v[178:181], v[82:85]
	v_mfma_f32_16x16x32_bf16 v[82:85], v[158:161], v[182:185], v[82:85]
	v_mfma_f32_16x16x32_bf16 v[70:73], v[146:149], v[186:189], v[70:73]
	v_mfma_f32_16x16x32_bf16 v[70:73], v[150:153], v[190:193], v[70:73]
	v_mfma_f32_16x16x32_bf16 v[66:69], v[154:157], v[186:189], v[66:69]
	v_mfma_f32_16x16x32_bf16 v[66:69], v[158:161], v[190:193], v[66:69]
	s_setprio 0
	s_barrier
; #define PG8_STAGE(bufoff, gbase, voff) do { _Pragma("unroll") for (int _i = 0; _i < 2; ++_i) \
;         __builtin_amdgcn_global_load_lds((const unsigned*)((const char*)(gbase) + (voff)[_i]), (PG8_LAS unsigned*)(lds + (bufoff) + ldsw + _i * 8192), 16, 0, 0); } while (0)
; #define PG8_LDA(dst, b, h) do { _Pragma("unroll") for (int m = 0; m < 4; ++m) _Pragma("unroll") for (int k = 0; k < 2; ++k) dst[m][k] = *(const PG8_LAS bf16x8*)(lds + PG8_SA(b, h) + aoff + m * 2048 + k * 1024); } while (0)
; #define PG8_MMA(ai, bj, At, Bt) do { __builtin_amdgcn_s_setprio(1); _Pragma("unroll") for (int m = 0; m < 4; ++m) _Pragma("unroll") for (int n = 0; n < 2; ++n) _Pragma("unroll") for (int k = 0; k < 2; ++k) \
;         acc[ai][bj][m][n] = __builtin_amdgcn_mfma_f32_16x16x32_bf16(Bt[n][k], At[m][k], acc[ai][bj][m][n], 0, 0, 0); __builtin_amdgcn_s_setprio(0); } while (0)
; #define PG8_WAIT_V(n) asm volatile("s_waitcnt vmcnt(" #n ")" ::: "memory")
; #define PG8_WAIT_L(n) asm volatile("s_waitcnt lgkmcnt(" #n ")" ::: "memory")
; #define PG8_BAR __builtin_amdgcn_s_barrier()
; #define PG8_SCHED __builtin_amdgcn_sched_barrier(0)
; template <class Epi, class Sched, bool ALIGN_EPI = false, bool SP2 = false>
; __device__ __forceinline__ void gemm_phase(PG8_LAS unsigned char* lds, const Gemm g, const Sched& S, const Epi& E) {
;     ...
;             PG8_LDA(At, 1, 1); PG8_STAGE(PG8_SB(1, 0), b3, voffB); PG8_STAGE(PG8_SB(1, 1), b3 + hstep, voffB); PG8_STAGE(PG8_SA(1, 0), a3, voffA);
;             PG8_WAIT_V(8); PG8_WAIT_L(0); PG8_BAR; PG8_MMA(1, 0, At, B0); PG8_MMA(1, 1, At, B1); PG8_BAR; PG8_SCHED;
	s_add_i32 s18, s18, s6
	v_lshl_add_u64 v[210:211], v[210:211], 0, s[30:31]
	s_mov_b32 m0, s18
	ds_read_b128 v[162:165], v247 offset:49152
	ds_read_b128 v[166:169], v247 offset:50176
	ds_read_b128 v[170:173], v247 offset:51200
	ds_read_b128 v[174:177], v247 offset:52224
	ds_read_b128 v[178:181], v247 offset:53248
	ds_read_b128 v[182:185], v247 offset:54272
	ds_read_b128 v[186:189], v247 offset:55296
	ds_read_b128 v[190:193], v247 offset:56320
	global_load_lds_dwordx4 v[210:211], off
	v_lshl_add_u64 v[210:211], v[212:213], 0, s[30:31]
	s_add_i32 m0, s18, 0x2000
	s_add_i32 s18, vcc_hi, s6
	global_load_lds_dwordx4 v[210:211], off
	v_lshl_add_u64 v[210:211], v[214:215], 0, s[30:31]
	s_mov_b32 m0, s18
	s_nop 0
	global_load_lds_dwordx4 v[210:211], off
	v_lshl_add_u64 v[210:211], v[216:217], 0, s[30:31]
	s_add_i32 m0, s18, 0x2000
	s_nop 0
	global_load_lds_dwordx4 v[210:211], off
	v_lshl_add_u64 v[210:211], v[218:219], 0, s[30:31]
	s_mov_b32 m0, s97
	s_nop 0
	global_load_lds_dwordx4 v[210:211], off
	v_lshl_add_u64 v[210:211], v[220:221], 0, s[30:31]
	s_mov_b32 m0, s98
	s_nop 0
	global_load_lds_dwordx4 v[210:211], off
	s_waitcnt vmcnt(8)
	s_waitcnt lgkmcnt(0)
	s_barrier
	s_setprio 1
	s_waitcnt lgkmcnt(0)
	v_mfma_f32_16x16x32_bf16 v[62:65], v[110:113], v[162:165], v[62:65]
	v_mfma_f32_16x16x32_bf16 v[62:65], v[118:121], v[166:169], v[62:65]
	v_mfma_f32_16x16x32_bf16 v[58:61], v[138:141], v[162:165], v[58:61]
	v_mfma_f32_16x16x32_bf16 v[58:61], v[142:145], v[166:169], v[58:61]
	v_mfma_f32_16x16x32_bf16 v[46:49], v[110:113], v[170:173], v[46:49]
	v_mfma_f32_16x16x32_bf16 v[46:49], v[118:121], v[174:177], v[46:49]
	v_mfma_f32_16x16x32_bf16 v[42:45], v[138:141], v[170:173], v[42:45]
	v_mfma_f32_16x16x32_bf16 v[42:45], v[142:145], v[174:177], v[42:45]
	v_mfma_f32_16x16x32_bf16 v[30:33], v[110:113], v[178:181], v[30:33]
	v_mfma_f32_16x16x32_bf16 v[30:33], v[118:121], v[182:185], v[30:33]
	v_mfma_f32_16x16x32_bf16 v[26:29], v[138:141], v[178:181], v[26:29]
	v_mfma_f32_16x16x32_bf16 v[26:29], v[142:145], v[182:185], v[26:29]
	v_mfma_f32_16x16x32_bf16 v[14:17], v[110:113], v[186:189], v[14:17]
	v_mfma_f32_16x16x32_bf16 v[14:17], v[118:121], v[190:193], v[14:17]
	v_mfma_f32_16x16x32_bf16 v[10:13], v[138:141], v[186:189], v[10:13]
	v_mfma_f32_16x16x32_bf16 v[10:13], v[142:145], v[190:193], v[10:13]
	s_setprio 0
	s_setprio 1
	v_mfma_f32_16x16x32_bf16 v[54:57], v[146:149], v[162:165], v[54:57]
	v_mfma_f32_16x16x32_bf16 v[54:57], v[150:153], v[166:169], v[54:57]
	v_mfma_f32_16x16x32_bf16 v[50:53], v[154:157], v[162:165], v[50:53]
	v_mfma_f32_16x16x32_bf16 v[50:53], v[158:161], v[166:169], v[50:53]
	v_mfma_f32_16x16x32_bf16 v[38:41], v[146:149], v[170:173], v[38:41]
	v_mfma_f32_16x16x32_bf16 v[38:41], v[150:153], v[174:177], v[38:41]
	v_mfma_f32_16x16x32_bf16 v[34:37], v[154:157], v[170:173], v[34:37]
	v_mfma_f32_16x16x32_bf16 v[34:37], v[158:161], v[174:177], v[34:37]
	v_mfma_f32_16x16x32_bf16 v[22:25], v[146:149], v[178:181], v[22:25]
	v_mfma_f32_16x16x32_bf16 v[22:25], v[150:153], v[182:185], v[22:25]
	v_mfma_f32_16x16x32_bf16 v[18:21], v[154:157], v[178:181], v[18:21]
	v_mfma_f32_16x16x32_bf16 v[18:21], v[158:161], v[182:185], v[18:21]
	v_mfma_f32_16x16x32_bf16 v[6:9], v[146:149], v[186:189], v[6:9]
	v_mfma_f32_16x16x32_bf16 v[6:9], v[150:153], v[190:193], v[6:9]
	v_mfma_f32_16x16x32_bf16 v[2:5], v[154:157], v[186:189], v[2:5]
	v_mfma_f32_16x16x32_bf16 v[2:5], v[158:161], v[190:193], v[2:5]
	s_setprio 0
	s_barrier
	s_add_u32 s48, s48, 0x100
	s_addc_u32 s49, s49, 0
	s_add_u32 s50, s50, 0x100
	s_addc_u32 s51, s51, 0
	s_cmp_ge_u32 vcc_lo, s96
	s_mov_b32 s46, vcc_lo
	s_cbranch_scc0 .LBB0_274
	s_and_b64 vcc, exec, s[72:73]
	s_cbranch_vccz .LBB0_277
	s_barrier

; #define PG8_STAGE(bufoff, gbase, voff) do { _Pragma("unroll") for (int _i = 0; _i < 2; ++_i) \
;         __builtin_amdgcn_global_load_lds((const unsigned*)((const char*)(gbase) + (voff)[_i]), (PG8_LAS unsigned*)(lds + (bufoff) + ldsw + _i * 8192), 16, 0, 0); } while (0)
; #define PG8_LDA(dst, b, h) do { _Pragma("unroll") for (int m = 0; m < 4; ++m) _Pragma("unroll") for (int k = 0; k < 2; ++k) dst[m][k] = *(const PG8_LAS bf16x8*)(lds + PG8_SA(b, h) + aoff + m * 2048 + k * 1024); } while (0)
; #define PG8_LDB(dst, b, h) do { _Pragma("unroll") for (int n = 0; n < 2; ++n) _Pragma("unroll") for (int k = 0; k < 2; ++k) dst[n][k] = *(const PG8_LAS bf16x8*)(lds + PG8_SB(b, h) + boff + n * 2048 + k * 1024); } while (0)
; #define PG8_MMA(ai, bj, At, Bt) do { __builtin_amdgcn_s_setprio(1); _Pragma("unroll") for (int m = 0; m < 4; ++m) _Pragma("unroll") for (int n = 0; n < 2; ++n) _Pragma("unroll") for (int k = 0; k < 2; ++k) \
;         acc[ai][bj][m][n] = __builtin_amdgcn_mfma_f32_16x16x32_bf16(Bt[n][k], At[m][k], acc[ai][bj][m][n], 0, 0, 0); __builtin_amdgcn_s_setprio(0); } while (0)
; #define PG8_WAIT_V(n) asm volatile("s_waitcnt vmcnt(" #n ")" ::: "memory")
; #define PG8_WAIT_L(n) asm volatile("s_waitcnt lgkmcnt(" #n ")" ::: "memory")
; #define PG8_BAR __builtin_amdgcn_s_barrier()
; #define PG8_SCHED __builtin_amdgcn_sched_barrier(0)
; template <class Epi, class Sched, bool ALIGN_EPI = false, bool SP2 = false>
; __device__ __forceinline__ void gemm_phase(PG8_LAS unsigned char* lds, const Gemm g, const Sched& S, const Epi& E) {
;     ...
;             const bool last = (t == nt - 2);
;             const char* a1 = cA + (size_t)(t + 1) * kstep;
;             const char* a2 = last ? nA : cA + (size_t)(t + 2) * kstep; const char* b2 = last ? nB : cB + (size_t)(t + 2) * kstep;
;             const char* a3 = a2 + kstep; const char* b3 = b2 + kstep;
;             if (last && has_next) S.a_ready(nxt);
;             if constexpr (SP2) {
;             PG8_LDB(B0, 0, 0); PG8_LDB(B1, 0, 1); PG8_SCHED; PG8_LDA(At, 0, 0); PG8_STAGE(PG8_SA(1, 1), a1 + hstep, voffA);
;             PG8_WAIT_V(8); PG8_WAIT_L(0); PG8_BAR; PG8_MMA(0, 0, At, B0); PG8_MMA(0, 1, At, B1); PG8_BAR; PG8_SCHED;
;             PG8_LDA(At, 0, 1); PG8_STAGE(PG8_SB(0, 0), b2, voffB); PG8_STAGE(PG8_SB(0, 1), b2 + hstep, voffB); PG8_STAGE(PG8_SA(0, 0), a2, voffA);
.LBB0_408:
	s_add_u32 s38, s48, 0xfffc0080
	s_addc_u32 s39, s49, -1
	s_add_i32 s85, 0, 0x10000
	s_cmp_eq_u32 s84, 12
	s_cselect_b32 s73, s21, s39
	s_cselect_b32 s72, s27, s38
	v_add_u32_e32 v0, s85, v167
	s_cselect_b32 s47, s29, s69
	s_cselect_b32 s46, s33, s53
	s_add_i32 s38, 0, 0x14000
	ds_read_b128 v[142:145], v0
	ds_read_b128 v[146:149], v0 offset:1024
	ds_read_b128 v[150:153], v0 offset:2048
	ds_read_b128 v[154:157], v0 offset:3072
	v_add_u32_e32 v0, s38, v167
	ds_read_b128 v[158:161], v0
	ds_read_b128 v[162:165], v0 offset:1024
	ds_read_b128 v[172:175], v0 offset:2048
	ds_read_b128 v[176:179], v0 offset:3072
	v_lshl_add_u64 v[218:219], s[48:49], 0, v[138:139]
	s_add_i32 m0, s76, 0xc000
	ds_read_b128 v[180:183], v170
	ds_read_b128 v[184:187], v170 offset:1024
	ds_read_b128 v[188:191], v170 offset:2048
	ds_read_b128 v[192:195], v170 offset:3072
	ds_read_b128 v[202:205], v170 offset:4096
	ds_read_b128 v[206:209], v170 offset:5120
	ds_read_b128 v[210:213], v170 offset:6144
	ds_read_b128 v[214:217], v170 offset:7168
	global_load_lds_dwordx4 v[218:219], off
	v_lshl_add_u64 v[218:219], s[48:49], 0, v[140:141]
	s_add_i32 m0, s76, 0xe000
	s_nop 0
	global_load_lds_dwordx4 v[218:219], off
	s_waitcnt vmcnt(8)
	s_waitcnt lgkmcnt(0)
	s_barrier
	s_setprio 1
	s_waitcnt lgkmcnt(0)
	v_mfma_f32_16x16x32_bf16 v[122:125], v[142:145], v[180:183], v[122:125]
	v_mfma_f32_16x16x32_bf16 v[122:125], v[146:149], v[184:187], v[122:125]
	v_mfma_f32_16x16x32_bf16 v[126:129], v[150:153], v[180:183], v[126:129]
	v_mfma_f32_16x16x32_bf16 v[126:129], v[154:157], v[184:187], v[126:129]
	v_mfma_f32_16x16x32_bf16 v[106:109], v[142:145], v[188:191], v[106:109]
	v_mfma_f32_16x16x32_bf16 v[106:109], v[146:149], v[192:195], v[106:109]
	v_mfma_f32_16x16x32_bf16 v[110:113], v[150:153], v[188:191], v[110:113]
	v_mfma_f32_16x16x32_bf16 v[110:113], v[154:157], v[192:195], v[110:113]
	v_mfma_f32_16x16x32_bf16 v[90:93], v[142:145], v[202:205], v[90:93]
	v_mfma_f32_16x16x32_bf16 v[90:93], v[146:149], v[206:209], v[90:93]
	v_mfma_f32_16x16x32_bf16 v[94:97], v[150:153], v[202:205], v[94:97]
	v_mfma_f32_16x16x32_bf16 v[94:97], v[154:157], v[206:209], v[94:97]
	v_mfma_f32_16x16x32_bf16 v[74:77], v[142:145], v[210:213], v[74:77]
	v_mfma_f32_16x16x32_bf16 v[74:77], v[146:149], v[214:217], v[74:77]
	v_mfma_f32_16x16x32_bf16 v[78:81], v[150:153], v[210:213], v[78:81]
	v_mfma_f32_16x16x32_bf16 v[78:81], v[154:157], v[214:217], v[78:81]
	s_setprio 0
	s_setprio 1
	v_mfma_f32_16x16x32_bf16 v[114:117], v[158:161], v[180:183], v[114:117]
	v_mfma_f32_16x16x32_bf16 v[114:117], v[162:165], v[184:187], v[114:117]
	v_mfma_f32_16x16x32_bf16 v[118:121], v[172:175], v[180:183], v[118:121]
	v_mfma_f32_16x16x32_bf16 v[118:121], v[176:179], v[184:187], v[118:121]
	v_mfma_f32_16x16x32_bf16 v[98:101], v[158:161], v[188:191], v[98:101]
	v_mfma_f32_16x16x32_bf16 v[98:101], v[162:165], v[192:195], v[98:101]
	v_mfma_f32_16x16x32_bf16 v[102:105], v[172:175], v[188:191], v[102:105]
	v_mfma_f32_16x16x32_bf16 v[102:105], v[176:179], v[192:195], v[102:105]
	v_mfma_f32_16x16x32_bf16 v[82:85], v[158:161], v[202:205], v[82:85]
	v_mfma_f32_16x16x32_bf16 v[82:85], v[162:165], v[206:209], v[82:85]
	v_mfma_f32_16x16x32_bf16 v[86:89], v[172:175], v[202:205], v[86:89]
	v_mfma_f32_16x16x32_bf16 v[86:89], v[176:179], v[206:209], v[86:89]
	v_mfma_f32_16x16x32_bf16 v[66:69], v[158:161], v[210:213], v[66:69]
	v_mfma_f32_16x16x32_bf16 v[66:69], v[162:165], v[214:217], v[66:69]
	v_mfma_f32_16x16x32_bf16 v[70:73], v[172:175], v[210:213], v[70:73]
	v_mfma_f32_16x16x32_bf16 v[70:73], v[176:179], v[214:217], v[70:73]
	s_setprio 0
	s_barrier
	s_add_i32 s39, s85, s75
	v_lshl_add_u64 v[218:219], s[46:47], 0, v[134:135]
	s_mov_b32 m0, s39
	ds_read_b128 v[180:183], v170 offset:16384
	ds_read_b128 v[184:187], v170 offset:17408
	ds_read_b128 v[188:191], v170 offset:18432
	ds_read_b128 v[192:195], v170 offset:19456
	ds_read_b128 v[202:205], v170 offset:20480
	ds_read_b128 v[206:209], v170 offset:21504
	ds_read_b128 v[210:213], v170 offset:22528
	ds_read_b128 v[214:217], v170 offset:23552
	global_load_lds_dwordx4 v[218:219], off
	s_add_i32 m0, s39, 0x2000
	s_add_u32 s92, s46, 0x40000
	v_lshl_add_u64 v[220:221], s[46:47], 0, v[130:131]
	s_addc_u32 s93, s47, 0
	s_add_i32 s38, s38, s75
	global_load_lds_dwordx4 v[220:221], off
	v_lshl_add_u64 v[222:223], s[92:93], 0, v[134:135]
	s_mov_b32 m0, s38
	v_lshl_add_u64 v[224:225], s[72:73], 0, v[132:133]
	global_load_lds_dwordx4 v[222:223], off
	v_lshl_add_u64 v[222:223], s[92:93], 0, v[130:131]
	s_add_i32 m0, s38, 0x2000
	s_nop 0
	global_load_lds_dwordx4 v[222:223], off
	v_lshl_add_u64 v[222:223], s[72:73], 0, v[136:137]
	s_mov_b32 m0, s76
	s_nop 0
	global_load_lds_dwordx4 v[222:223], off
	s_mov_b32 m0, s77
	s_nop 0
	global_load_lds_dwordx4 v[224:225], off
	s_waitcnt vmcnt(8)
	s_waitcnt lgkmcnt(0)
	s_barrier
; #define PG8_STAGE(bufoff, gbase, voff) do { _Pragma("unroll") for (int _i = 0; _i < 2; ++_i) \
;         __builtin_amdgcn_global_load_lds((const unsigned*)((const char*)(gbase) + (voff)[_i]), (PG8_LAS unsigned*)(lds + (bufoff) + ldsw + _i * 8192), 16, 0, 0); } while (0)
; #define PG8_LDA(dst, b, h) do { _Pragma("unroll") for (int m = 0; m < 4; ++m) _Pragma("unroll") for (int k = 0; k < 2; ++k) dst[m][k] = *(const PG8_LAS bf16x8*)(lds + PG8_SA(b, h) + aoff + m * 2048 + k * 1024); } while (0)
; #define PG8_LDB(dst, b, h) do { _Pragma("unroll") for (int n = 0; n < 2; ++n) _Pragma("unroll") for (int k = 0; k < 2; ++k) dst[n][k] = *(const PG8_LAS bf16x8*)(lds + PG8_SB(b, h) + boff + n * 2048 + k * 1024); } while (0)
; #define PG8_MMA(ai, bj, At, Bt) do { __builtin_amdgcn_s_setprio(1); _Pragma("unroll") for (int m = 0; m < 4; ++m) _Pragma("unroll") for (int n = 0; n < 2; ++n) _Pragma("unroll") for (int k = 0; k < 2; ++k) \
;         acc[ai][bj][m][n] = __builtin_amdgcn_mfma_f32_16x16x32_bf16(Bt[n][k], At[m][k], acc[ai][bj][m][n], 0, 0, 0); __builtin_amdgcn_s_setprio(0); } while (0)
; #define PG8_WAIT_V(n) asm volatile("s_waitcnt vmcnt(" #n ")" ::: "memory")
; #define PG8_WAIT_L(n) asm volatile("s_waitcnt lgkmcnt(" #n ")" ::: "memory")
; #define PG8_BAR __builtin_amdgcn_s_barrier()
; #define PG8_SCHED __builtin_amdgcn_sched_barrier(0)
; template <class Epi, class Sched, bool ALIGN_EPI = false, bool SP2 = false>
; __device__ __forceinline__ void gemm_phase(PG8_LAS unsigned char* lds, const Gemm g, const Sched& S, const Epi& E) {
;     ...
;             PG8_WAIT_V(8); PG8_WAIT_L(0); PG8_BAR; PG8_MMA(1, 0, At, B0); PG8_MMA(1, 1, At, B1); PG8_BAR; PG8_SCHED;
;             PG8_LDB(B0, 1, 0); PG8_LDB(B1, 1, 1); PG8_SCHED; PG8_LDA(At, 1, 0); PG8_STAGE(PG8_SA(0, 1), a2 + hstep, voffA);
;             PG8_WAIT_V(8); PG8_WAIT_L(0); PG8_BAR; PG8_MMA(0, 0, At, B0); PG8_MMA(0, 1, At, B1); PG8_BAR; PG8_SCHED;
	s_setprio 1
	s_waitcnt lgkmcnt(0)
	v_mfma_f32_16x16x32_bf16 v[58:61], v[142:145], v[180:183], v[58:61]
	v_mfma_f32_16x16x32_bf16 v[58:61], v[146:149], v[184:187], v[58:61]
	v_mfma_f32_16x16x32_bf16 v[62:65], v[150:153], v[180:183], v[62:65]
	v_mfma_f32_16x16x32_bf16 v[62:65], v[154:157], v[184:187], v[62:65]
	v_mfma_f32_16x16x32_bf16 v[42:45], v[142:145], v[188:191], v[42:45]
	v_mfma_f32_16x16x32_bf16 v[42:45], v[146:149], v[192:195], v[42:45]
	v_mfma_f32_16x16x32_bf16 v[46:49], v[150:153], v[188:191], v[46:49]
	v_mfma_f32_16x16x32_bf16 v[46:49], v[154:157], v[192:195], v[46:49]
	v_mfma_f32_16x16x32_bf16 v[26:29], v[142:145], v[202:205], v[26:29]
	v_mfma_f32_16x16x32_bf16 v[26:29], v[146:149], v[206:209], v[26:29]
	v_mfma_f32_16x16x32_bf16 v[30:33], v[150:153], v[202:205], v[30:33]
	v_mfma_f32_16x16x32_bf16 v[30:33], v[154:157], v[206:209], v[30:33]
	v_mfma_f32_16x16x32_bf16 v[10:13], v[142:145], v[210:213], v[10:13]
	v_mfma_f32_16x16x32_bf16 v[10:13], v[146:149], v[214:217], v[10:13]
	v_mfma_f32_16x16x32_bf16 v[14:17], v[150:153], v[210:213], v[14:17]
	v_mfma_f32_16x16x32_bf16 v[14:17], v[154:157], v[214:217], v[14:17]
	s_setprio 0
	s_setprio 1
	v_mfma_f32_16x16x32_bf16 v[50:53], v[158:161], v[180:183], v[50:53]
	v_mfma_f32_16x16x32_bf16 v[50:53], v[162:165], v[184:187], v[50:53]
	v_mfma_f32_16x16x32_bf16 v[54:57], v[172:175], v[180:183], v[54:57]
	v_mfma_f32_16x16x32_bf16 v[54:57], v[176:179], v[184:187], v[54:57]
	v_mfma_f32_16x16x32_bf16 v[34:37], v[158:161], v[188:191], v[34:37]
	v_mfma_f32_16x16x32_bf16 v[34:37], v[162:165], v[192:195], v[34:37]
	v_mfma_f32_16x16x32_bf16 v[38:41], v[172:175], v[188:191], v[38:41]
	v_mfma_f32_16x16x32_bf16 v[38:41], v[176:179], v[192:195], v[38:41]
	v_mfma_f32_16x16x32_bf16 v[18:21], v[158:161], v[202:205], v[18:21]
	v_mfma_f32_16x16x32_bf16 v[18:21], v[162:165], v[206:209], v[18:21]
	v_mfma_f32_16x16x32_bf16 v[22:25], v[172:175], v[202:205], v[22:25]
	v_mfma_f32_16x16x32_bf16 v[22:25], v[176:179], v[206:209], v[22:25]
	v_mfma_f32_16x16x32_bf16 v[2:5], v[158:161], v[210:213], v[2:5]
	v_mfma_f32_16x16x32_bf16 v[2:5], v[162:165], v[214:217], v[2:5]
	v_mfma_f32_16x16x32_bf16 v[6:9], v[172:175], v[210:213], v[6:9]
	v_mfma_f32_16x16x32_bf16 v[6:9], v[176:179], v[214:217], v[6:9]
	s_setprio 0
	s_barrier
	s_add_i32 s38, 0, 0x18000
	v_add_u32_e32 v0, s38, v167
	s_add_i32 s39, 0, 0x1c000
	ds_read_b128 v[142:145], v0
	ds_read_b128 v[146:149], v0 offset:1024
	ds_read_b128 v[150:153], v0 offset:2048
	ds_read_b128 v[154:157], v0 offset:3072
	v_add_u32_e32 v0, s39, v167
	ds_read_b128 v[158:161], v0
	ds_read_b128 v[162:165], v0 offset:1024
	ds_read_b128 v[172:175], v0 offset:2048
	ds_read_b128 v[176:179], v0 offset:3072
	s_add_u32 s72, s72, 0x40000
	s_addc_u32 s73, s73, 0
	s_mov_b32 m0, s78
	v_lshl_add_u64 v[226:227], s[72:73], 0, v[136:137]
	ds_read_b128 v[180:183], v170 offset:32768
	ds_read_b128 v[184:187], v170 offset:33792
	ds_read_b128 v[188:191], v170 offset:34816
	ds_read_b128 v[192:195], v170 offset:35840
	ds_read_b128 v[202:205], v170 offset:36864
	ds_read_b128 v[206:209], v170 offset:37888
	ds_read_b128 v[210:213], v170 offset:38912
	ds_read_b128 v[214:217], v170 offset:39936
	global_load_lds_dwordx4 v[226:227], off
	v_lshl_add_u64 v[226:227], s[72:73], 0, v[132:133]
	s_mov_b32 m0, s79
	s_nop 0
	global_load_lds_dwordx4 v[226:227], off
	s_waitcnt vmcnt(8)
	s_waitcnt lgkmcnt(0)
	s_barrier
	s_setprio 1
	s_waitcnt lgkmcnt(0)
	v_mfma_f32_16x16x32_bf16 v[122:125], v[142:145], v[180:183], v[122:125]
	v_mfma_f32_16x16x32_bf16 v[122:125], v[146:149], v[184:187], v[122:125]
	v_mfma_f32_16x16x32_bf16 v[126:129], v[150:153], v[180:183], v[126:129]
	v_mfma_f32_16x16x32_bf16 v[126:129], v[154:157], v[184:187], v[126:129]
	v_mfma_f32_16x16x32_bf16 v[106:109], v[142:145], v[188:191], v[106:109]
	v_mfma_f32_16x16x32_bf16 v[106:109], v[146:149], v[192:195], v[106:109]
	v_mfma_f32_16x16x32_bf16 v[110:113], v[150:153], v[188:191], v[110:113]
	v_mfma_f32_16x16x32_bf16 v[110:113], v[154:157], v[192:195], v[110:113]
	v_mfma_f32_16x16x32_bf16 v[90:93], v[142:145], v[202:205], v[90:93]
	v_mfma_f32_16x16x32_bf16 v[90:93], v[146:149], v[206:209], v[90:93]
	v_mfma_f32_16x16x32_bf16 v[94:97], v[150:153], v[202:205], v[94:97]
	v_mfma_f32_16x16x32_bf16 v[94:97], v[154:157], v[206:209], v[94:97]
	v_mfma_f32_16x16x32_bf16 v[74:77], v[142:145], v[210:213], v[74:77]
	v_mfma_f32_16x16x32_bf16 v[74:77], v[146:149], v[214:217], v[74:77]
	v_mfma_f32_16x16x32_bf16 v[78:81], v[150:153], v[210:213], v[78:81]
	v_mfma_f32_16x16x32_bf16 v[78:81], v[154:157], v[214:217], v[78:81]
	s_setprio 0
	s_setprio 1
	v_mfma_f32_16x16x32_bf16 v[114:117], v[158:161], v[180:183], v[114:117]
	v_mfma_f32_16x16x32_bf16 v[114:117], v[162:165], v[184:187], v[114:117]
	v_mfma_f32_16x16x32_bf16 v[118:121], v[172:175], v[180:183], v[118:121]
	v_mfma_f32_16x16x32_bf16 v[118:121], v[176:179], v[184:187], v[118:121]
	v_mfma_f32_16x16x32_bf16 v[98:101], v[158:161], v[188:191], v[98:101]
	v_mfma_f32_16x16x32_bf16 v[98:101], v[162:165], v[192:195], v[98:101]
	v_mfma_f32_16x16x32_bf16 v[102:105], v[172:175], v[188:191], v[102:105]
	v_mfma_f32_16x16x32_bf16 v[102:105], v[176:179], v[192:195], v[102:105]
	v_mfma_f32_16x16x32_bf16 v[82:85], v[158:161], v[202:205], v[82:85]
	v_mfma_f32_16x16x32_bf16 v[82:85], v[162:165], v[206:209], v[82:85]
	v_mfma_f32_16x16x32_bf16 v[86:89], v[172:175], v[202:205], v[86:89]
	v_mfma_f32_16x16x32_bf16 v[86:89], v[176:179], v[206:209], v[86:89]
	v_mfma_f32_16x16x32_bf16 v[66:69], v[158:161], v[210:213], v[66:69]
	v_mfma_f32_16x16x32_bf16 v[66:69], v[162:165], v[214:217], v[66:69]
	v_mfma_f32_16x16x32_bf16 v[70:73], v[172:175], v[210:213], v[70:73]
	v_mfma_f32_16x16x32_bf16 v[70:73], v[176:179], v[214:217], v[70:73]
	s_setprio 0
	s_barrier
; #define PG8_STAGE(bufoff, gbase, voff) do { _Pragma("unroll") for (int _i = 0; _i < 2; ++_i) \
;         __builtin_amdgcn_global_load_lds((const unsigned*)((const char*)(gbase) + (voff)[_i]), (PG8_LAS unsigned*)(lds + (bufoff) + ldsw + _i * 8192), 16, 0, 0); } while (0)
; #define PG8_LDA(dst, b, h) do { _Pragma("unroll") for (int m = 0; m < 4; ++m) _Pragma("unroll") for (int k = 0; k < 2; ++k) dst[m][k] = *(const PG8_LAS bf16x8*)(lds + PG8_SA(b, h) + aoff + m * 2048 + k * 1024); } while (0)
; #define PG8_MMA(ai, bj, At, Bt) do { __builtin_amdgcn_s_setprio(1); _Pragma("unroll") for (int m = 0; m < 4; ++m) _Pragma("unroll") for (int n = 0; n < 2; ++n) _Pragma("unroll") for (int k = 0; k < 2; ++k) \
;         acc[ai][bj][m][n] = __builtin_amdgcn_mfma_f32_16x16x32_bf16(Bt[n][k], At[m][k], acc[ai][bj][m][n], 0, 0, 0); __builtin_amdgcn_s_setprio(0); } while (0)
; #define PG8_WAIT_V(n) asm volatile("s_waitcnt vmcnt(" #n ")" ::: "memory")
; #define PG8_WAIT_L(n) asm volatile("s_waitcnt lgkmcnt(" #n ")" ::: "memory")
; #define PG8_BAR __builtin_amdgcn_s_barrier()
; #define PG8_SCHED __builtin_amdgcn_sched_barrier(0)
; template <class Epi, class Sched, bool ALIGN_EPI = false, bool SP2 = false>
; __device__ __forceinline__ void gemm_phase(PG8_LAS unsigned char* lds, const Gemm g, const Sched& S, const Epi& E) {
;     ...
;             PG8_LDA(At, 1, 1); PG8_STAGE(PG8_SB(1, 0), b3, voffB); PG8_STAGE(PG8_SB(1, 1), b3 + hstep, voffB); PG8_STAGE(PG8_SA(1, 0), a3, voffA);
;             PG8_WAIT_V(8); PG8_WAIT_L(0); PG8_BAR; PG8_MMA(1, 0, At, B0); PG8_MMA(1, 1, At, B1); PG8_BAR; PG8_SCHED;
	s_add_i32 s38, s38, s75
	v_lshl_add_u64 v[218:219], v[218:219], 0, s[30:31]
	s_mov_b32 m0, s38
	ds_read_b128 v[180:183], v170 offset:49152
	ds_read_b128 v[184:187], v170 offset:50176
	ds_read_b128 v[188:191], v170 offset:51200
	ds_read_b128 v[192:195], v170 offset:52224
	ds_read_b128 v[202:205], v170 offset:53248
	ds_read_b128 v[206:209], v170 offset:54272
	ds_read_b128 v[210:213], v170 offset:55296
	ds_read_b128 v[214:217], v170 offset:56320
	global_load_lds_dwordx4 v[218:219], off
	s_add_i32 m0, s38, 0x2000
	s_add_u32 s46, s46, 0x40080
	v_lshl_add_u64 v[218:219], v[220:221], 0, s[30:31]
	s_addc_u32 s47, s47, 0
	s_add_i32 s38, s39, s75
	global_load_lds_dwordx4 v[218:219], off
	v_lshl_add_u64 v[218:219], s[46:47], 0, v[134:135]
	s_mov_b32 m0, s38
	s_nop 0
	global_load_lds_dwordx4 v[218:219], off
	v_lshl_add_u64 v[218:219], s[46:47], 0, v[130:131]
	s_add_i32 m0, s38, 0x2000
	s_nop 0
	global_load_lds_dwordx4 v[218:219], off
	v_lshl_add_u64 v[218:219], v[222:223], 0, s[30:31]
	s_mov_b32 m0, s80
	s_nop 0
	global_load_lds_dwordx4 v[218:219], off
	v_lshl_add_u64 v[218:219], v[224:225], 0, s[30:31]
	s_mov_b32 m0, s81
	s_nop 0
	global_load_lds_dwordx4 v[218:219], off
	s_waitcnt vmcnt(8)
	s_waitcnt lgkmcnt(0)
	s_barrier
	s_setprio 1
	s_waitcnt lgkmcnt(0)
	v_mfma_f32_16x16x32_bf16 v[58:61], v[142:145], v[180:183], v[58:61]
	v_mfma_f32_16x16x32_bf16 v[58:61], v[146:149], v[184:187], v[58:61]
	v_mfma_f32_16x16x32_bf16 v[62:65], v[150:153], v[180:183], v[62:65]
	v_mfma_f32_16x16x32_bf16 v[62:65], v[154:157], v[184:187], v[62:65]
	v_mfma_f32_16x16x32_bf16 v[42:45], v[142:145], v[188:191], v[42:45]
	v_mfma_f32_16x16x32_bf16 v[42:45], v[146:149], v[192:195], v[42:45]
	v_mfma_f32_16x16x32_bf16 v[46:49], v[150:153], v[188:191], v[46:49]
	v_mfma_f32_16x16x32_bf16 v[46:49], v[154:157], v[192:195], v[46:49]
	v_mfma_f32_16x16x32_bf16 v[26:29], v[142:145], v[202:205], v[26:29]
	v_mfma_f32_16x16x32_bf16 v[26:29], v[146:149], v[206:209], v[26:29]
	v_mfma_f32_16x16x32_bf16 v[30:33], v[150:153], v[202:205], v[30:33]
	v_mfma_f32_16x16x32_bf16 v[30:33], v[154:157], v[206:209], v[30:33]
	v_mfma_f32_16x16x32_bf16 v[10:13], v[142:145], v[210:213], v[10:13]
	v_mfma_f32_16x16x32_bf16 v[10:13], v[146:149], v[214:217], v[10:13]
	v_mfma_f32_16x16x32_bf16 v[14:17], v[150:153], v[210:213], v[14:17]
	v_mfma_f32_16x16x32_bf16 v[14:17], v[154:157], v[214:217], v[14:17]
	s_setprio 0
	s_setprio 1
	v_mfma_f32_16x16x32_bf16 v[50:53], v[158:161], v[180:183], v[50:53]
	v_mfma_f32_16x16x32_bf16 v[50:53], v[162:165], v[184:187], v[50:53]
	v_mfma_f32_16x16x32_bf16 v[54:57], v[172:175], v[180:183], v[54:57]
	v_mfma_f32_16x16x32_bf16 v[54:57], v[176:179], v[184:187], v[54:57]
	v_mfma_f32_16x16x32_bf16 v[34:37], v[158:161], v[188:191], v[34:37]
	v_mfma_f32_16x16x32_bf16 v[34:37], v[162:165], v[192:195], v[34:37]
	v_mfma_f32_16x16x32_bf16 v[38:41], v[172:175], v[188:191], v[38:41]
	v_mfma_f32_16x16x32_bf16 v[38:41], v[176:179], v[192:195], v[38:41]
	v_mfma_f32_16x16x32_bf16 v[18:21], v[158:161], v[202:205], v[18:21]
	v_mfma_f32_16x16x32_bf16 v[18:21], v[162:165], v[206:209], v[18:21]
	v_mfma_f32_16x16x32_bf16 v[22:25], v[172:175], v[202:205], v[22:25]
	v_mfma_f32_16x16x32_bf16 v[22:25], v[176:179], v[206:209], v[22:25]
	v_mfma_f32_16x16x32_bf16 v[2:5], v[158:161], v[210:213], v[2:5]
	v_mfma_f32_16x16x32_bf16 v[2:5], v[162:165], v[214:217], v[2:5]
	v_mfma_f32_16x16x32_bf16 v[6:9], v[172:175], v[210:213], v[6:9]
	v_mfma_f32_16x16x32_bf16 v[6:9], v[176:179], v[214:217], v[6:9]
	s_setprio 0
	s_barrier
	s_add_i32 s84, s84, 2
	s_add_u32 s48, s48, 0x100
	s_addc_u32 s49, s49, 0
	s_add_u32 s53, s53, 0x100
	s_addc_u32 s69, s69, 0
	s_cmp_gt_u32 s84, 13
	s_cbranch_scc0 .LBB0_408
	s_and_b64 vcc, exec, s[64:65]
	s_cbranch_vccz .LBB0_411
	s_barrier
